# seq unit XCD remap + gla_seq store-aware vmcnt counts + EPI2 epilogue loads hoisted (counted waits)
# baseline (speedup 1.0000x reference)
; __device__ __forceinline__ unsigned pack2(float a, float b) { f32v2_t v = {a, b}; bf16v2_t r = __builtin_convertvector(v, bf16v2_t); return __builtin_bit_cast(unsigned, r); }
; template <int EPI, int N, int K>
; __device__ __forceinline__ void gemm_phase(const KP& p, int l, const bfr* A, const bfr* Bt) {
;     ...
;     } else if (EPI == 2) {
;       bfr* hb = (bfr*)(p.ws + OFF_HB);
; #pragma unroll
;       for (int ai = 0; ai < 2; ++ai)
; #pragma unroll
;         for (int m = 0; m < 4; ++m) {
;           int row = erow + ai * HM + wr * 64 + m * 16 + fr;
; #pragma unroll
;           for (int bj = 0; bj < 2; ++bj) {
;             u32x4* hp = (u32x4*)(hb + (size_t)row * DM + ecol + bj * HALF + wc * 32 + fq * 8);
;             u32x4 h = *hp, o;
; #pragma unroll
;             for (int q2 = 0; q2 < 4; ++q2) {
;               f32v2_t hv2 = {__uint_as_float(h[q2] << 16), __uint_as_float(h[q2] & 0xffff0000u)};
;               f32v2_t av2 = {acc[ai][bj][m][q2 >> 1][(q2 & 1) * 2], acc[ai][bj][m][q2 >> 1][(q2 & 1) * 2 + 1]};
;               f32v2_t s2 = hv2 + av2;
;               o[q2] = pack2(s2.x, s2.y);
;             }
;             *hp = o;
;           }
;         }
.LBB0_297:
	v_add_u32_e32 v134, s52, v147
	v_ashrrev_i32_e32 v135, 31, v134
	v_lshl_add_u64 v[132:133], s[74:75], 1, v[130:131]
	v_lshlrev_b64 v[166:167], 11, v[134:135]
	v_lshl_add_u64 v[166:167], v[132:133], 0, v[166:167]
	s_andn2_b64 vcc, exec, s[46:47]
	s_mov_b32 s52, s50
	s_mov_b64 s[98:99], 0x8000
	s_mov_b64 s[100:101], 0x28000
	v_lshl_add_u64 v[242:243], v[166:167], 0, s[98:99]
	v_lshl_add_u64 v[244:245], v[242:243], 0, s[98:99]
	v_lshl_add_u64 v[246:247], v[244:245], 0, s[98:99]
	v_lshl_add_u64 v[248:249], v[246:247], 0, s[100:101]
	v_lshl_add_u64 v[250:251], v[248:249], 0, s[98:99]
	v_lshl_add_u64 v[252:253], v[250:251], 0, s[98:99]
	v_lshl_add_u64 v[174:175], v[252:253], 0, s[98:99]
	global_load_dwordx4 v[178:181], v[166:167], off
	global_load_dwordx4 v[182:185], v[166:167], off offset:256
	global_load_dwordx4 v[186:189], v[242:243], off
	global_load_dwordx4 v[190:193], v[242:243], off offset:256
	global_load_dwordx4 v[194:197], v[244:245], off
	global_load_dwordx4 v[198:201], v[244:245], off offset:256
	global_load_dwordx4 v[202:205], v[246:247], off
	global_load_dwordx4 v[206:209], v[246:247], off offset:256
	global_load_dwordx4 v[210:213], v[248:249], off
	global_load_dwordx4 v[214:217], v[248:249], off offset:256
	global_load_dwordx4 v[218:221], v[250:251], off
	global_load_dwordx4 v[222:225], v[250:251], off offset:256
	global_load_dwordx4 v[226:229], v[252:253], off
	global_load_dwordx4 v[230:233], v[252:253], off offset:256
	global_load_dwordx4 v[234:237], v[174:175], off
	global_load_dwordx4 v[238:241], v[174:175], off offset:256
	s_waitcnt vmcnt(15)
	v_lshlrev_b32_e32 v168, 16, v178
	v_and_b32_e32 v169, 0xffff0000, v178
	v_lshlrev_b32_e32 v176, 16, v179
	v_and_b32_e32 v177, 0xffff0000, v179
	v_pk_add_f32 v[126:127], v[126:127], v[168:169]
	v_pk_add_f32 v[128:129], v[128:129], v[176:177]
	v_lshlrev_b32_e32 v168, 16, v180
	v_and_b32_e32 v169, 0xffff0000, v180
	v_lshlrev_b32_e32 v176, 16, v181
	v_and_b32_e32 v177, 0xffff0000, v181
	v_pk_add_f32 v[122:123], v[122:123], v[168:169]
	v_pk_add_f32 v[124:125], v[124:125], v[176:177]
	v_cvt_pk_bf16_f32 v178, v126, v127
	v_cvt_pk_bf16_f32 v179, v128, v129
	v_cvt_pk_bf16_f32 v180, v122, v123
	v_cvt_pk_bf16_f32 v181, v124, v125
	global_store_dwordx4 v[166:167], v[178:181], off
	s_waitcnt vmcnt(15)
	v_lshlrev_b32_e32 v168, 16, v182
	v_and_b32_e32 v169, 0xffff0000, v182
	v_lshlrev_b32_e32 v176, 16, v183
	v_and_b32_e32 v177, 0xffff0000, v183
	v_pk_add_f32 v[118:119], v[118:119], v[168:169]
	v_pk_add_f32 v[120:121], v[120:121], v[176:177]
	v_lshlrev_b32_e32 v168, 16, v184
	v_and_b32_e32 v169, 0xffff0000, v184
	v_lshlrev_b32_e32 v176, 16, v185
	v_and_b32_e32 v177, 0xffff0000, v185
	v_pk_add_f32 v[114:115], v[114:115], v[168:169]
	v_pk_add_f32 v[116:117], v[116:117], v[176:177]
	v_cvt_pk_bf16_f32 v182, v118, v119
	v_cvt_pk_bf16_f32 v183, v120, v121
	v_cvt_pk_bf16_f32 v184, v114, v115
	v_cvt_pk_bf16_f32 v185, v116, v117
	global_store_dwordx4 v[166:167], v[182:185], off offset:256
	s_waitcnt vmcnt(15)
	v_lshlrev_b32_e32 v168, 16, v186
	v_and_b32_e32 v169, 0xffff0000, v186
	v_lshlrev_b32_e32 v176, 16, v187
	v_and_b32_e32 v177, 0xffff0000, v187
	v_pk_add_f32 v[110:111], v[110:111], v[168:169]
	v_pk_add_f32 v[112:113], v[112:113], v[176:177]
	v_lshlrev_b32_e32 v168, 16, v188
	v_and_b32_e32 v169, 0xffff0000, v188
	v_lshlrev_b32_e32 v176, 16, v189
	v_and_b32_e32 v177, 0xffff0000, v189
	v_pk_add_f32 v[106:107], v[106:107], v[168:169]
	v_pk_add_f32 v[108:109], v[108:109], v[176:177]
	v_cvt_pk_bf16_f32 v186, v110, v111
	v_cvt_pk_bf16_f32 v187, v112, v113
	v_cvt_pk_bf16_f32 v188, v106, v107
	v_cvt_pk_bf16_f32 v189, v108, v109
	global_store_dwordx4 v[242:243], v[186:189], off
	s_waitcnt vmcnt(15)
	v_lshlrev_b32_e32 v168, 16, v190
	v_and_b32_e32 v169, 0xffff0000, v190
	v_lshlrev_b32_e32 v176, 16, v191
	v_and_b32_e32 v177, 0xffff0000, v191
	v_pk_add_f32 v[102:103], v[102:103], v[168:169]
	v_pk_add_f32 v[104:105], v[104:105], v[176:177]
	v_lshlrev_b32_e32 v168, 16, v192
	v_and_b32_e32 v169, 0xffff0000, v192
	v_lshlrev_b32_e32 v176, 16, v193
	v_and_b32_e32 v177, 0xffff0000, v193
	v_pk_add_f32 v[98:99], v[98:99], v[168:169]
	v_pk_add_f32 v[100:101], v[100:101], v[176:177]
	v_cvt_pk_bf16_f32 v190, v102, v103
	v_cvt_pk_bf16_f32 v191, v104, v105
	v_cvt_pk_bf16_f32 v192, v98, v99
	v_cvt_pk_bf16_f32 v193, v100, v101
	global_store_dwordx4 v[242:243], v[190:193], off offset:256
	s_waitcnt vmcnt(15)
	v_lshlrev_b32_e32 v168, 16, v194
	v_and_b32_e32 v169, 0xffff0000, v194
	v_lshlrev_b32_e32 v176, 16, v195
	v_and_b32_e32 v177, 0xffff0000, v195
	v_pk_add_f32 v[86:87], v[86:87], v[168:169]
	v_pk_add_f32 v[88:89], v[88:89], v[176:177]
	v_lshlrev_b32_e32 v168, 16, v196
	v_and_b32_e32 v169, 0xffff0000, v196
	v_lshlrev_b32_e32 v176, 16, v197
	v_and_b32_e32 v177, 0xffff0000, v197
	v_pk_add_f32 v[82:83], v[82:83], v[168:169]
	v_pk_add_f32 v[84:85], v[84:85], v[176:177]
	v_cvt_pk_bf16_f32 v194, v86, v87
	v_cvt_pk_bf16_f32 v195, v88, v89
	v_cvt_pk_bf16_f32 v196, v82, v83
	v_cvt_pk_bf16_f32 v197, v84, v85
	global_store_dwordx4 v[244:245], v[194:197], off
	s_waitcnt vmcnt(15)
	v_lshlrev_b32_e32 v168, 16, v198
	v_and_b32_e32 v169, 0xffff0000, v198
	v_lshlrev_b32_e32 v176, 16, v199
	v_and_b32_e32 v177, 0xffff0000, v199
	v_pk_add_f32 v[94:95], v[94:95], v[168:169]
	v_pk_add_f32 v[96:97], v[96:97], v[176:177]
	v_lshlrev_b32_e32 v168, 16, v200
	v_and_b32_e32 v169, 0xffff0000, v200
	v_lshlrev_b32_e32 v176, 16, v201
	v_and_b32_e32 v177, 0xffff0000, v201
	v_pk_add_f32 v[90:91], v[90:91], v[168:169]
	v_pk_add_f32 v[92:93], v[92:93], v[176:177]
	v_cvt_pk_bf16_f32 v198, v94, v95
	v_cvt_pk_bf16_f32 v199, v96, v97
	v_cvt_pk_bf16_f32 v200, v90, v91
	v_cvt_pk_bf16_f32 v201, v92, v93
	global_store_dwordx4 v[244:245], v[198:201], off offset:256
	s_waitcnt vmcnt(15)
; __device__ __forceinline__ unsigned pack2(float a, float b) { f32v2_t v = {a, b}; bf16v2_t r = __builtin_convertvector(v, bf16v2_t); return __builtin_bit_cast(unsigned, r); }
; template <int EPI, int N, int K>
; __device__ __forceinline__ void gemm_phase(const KP& p, int l, const bfr* A, const bfr* Bt) {
;     ...
;           int row = erow + ai * HM + wr * 64 + m * 16 + fr;
; #pragma unroll
;           for (int bj = 0; bj < 2; ++bj) {
;             u32x4* hp = (u32x4*)(hb + (size_t)row * DM + ecol + bj * HALF + wc * 32 + fq * 8);
;             u32x4 h = *hp, o;
; #pragma unroll
;             for (int q2 = 0; q2 < 4; ++q2) {
;               f32v2_t hv2 = {__uint_as_float(h[q2] << 16), __uint_as_float(h[q2] & 0xffff0000u)};
;               f32v2_t av2 = {acc[ai][bj][m][q2 >> 1][(q2 & 1) * 2], acc[ai][bj][m][q2 >> 1][(q2 & 1) * 2 + 1]};
;               f32v2_t s2 = hv2 + av2;
;               o[q2] = pack2(s2.x, s2.y);
;             }
;             *hp = o;
;           }
	v_lshlrev_b32_e32 v168, 16, v202
	v_and_b32_e32 v169, 0xffff0000, v202
	v_lshlrev_b32_e32 v176, 16, v203
	v_and_b32_e32 v177, 0xffff0000, v203
	v_pk_add_f32 v[78:79], v[78:79], v[168:169]
	v_pk_add_f32 v[80:81], v[80:81], v[176:177]
	v_lshlrev_b32_e32 v168, 16, v204
	v_and_b32_e32 v169, 0xffff0000, v204
	v_lshlrev_b32_e32 v176, 16, v205
	v_and_b32_e32 v177, 0xffff0000, v205
	v_pk_add_f32 v[74:75], v[74:75], v[168:169]
	v_pk_add_f32 v[76:77], v[76:77], v[176:177]
	v_cvt_pk_bf16_f32 v202, v78, v79
	v_cvt_pk_bf16_f32 v203, v80, v81
	v_cvt_pk_bf16_f32 v204, v74, v75
	v_cvt_pk_bf16_f32 v205, v76, v77
	global_store_dwordx4 v[246:247], v[202:205], off
	s_waitcnt vmcnt(15)
	v_lshlrev_b32_e32 v168, 16, v206
	v_and_b32_e32 v169, 0xffff0000, v206
	v_lshlrev_b32_e32 v176, 16, v207
	v_and_b32_e32 v177, 0xffff0000, v207
	v_pk_add_f32 v[70:71], v[70:71], v[168:169]
	v_pk_add_f32 v[72:73], v[72:73], v[176:177]
	v_lshlrev_b32_e32 v168, 16, v208
	v_and_b32_e32 v169, 0xffff0000, v208
	v_lshlrev_b32_e32 v176, 16, v209
	v_and_b32_e32 v177, 0xffff0000, v209
	v_pk_add_f32 v[66:67], v[66:67], v[168:169]
	v_pk_add_f32 v[68:69], v[68:69], v[176:177]
	v_cvt_pk_bf16_f32 v206, v70, v71
	v_cvt_pk_bf16_f32 v207, v72, v73
	v_cvt_pk_bf16_f32 v208, v66, v67
	v_cvt_pk_bf16_f32 v209, v68, v69
	global_store_dwordx4 v[246:247], v[206:209], off offset:256
	s_waitcnt vmcnt(15)
	v_lshlrev_b32_e32 v168, 16, v210
	v_and_b32_e32 v169, 0xffff0000, v210
	v_lshlrev_b32_e32 v176, 16, v211
	v_and_b32_e32 v177, 0xffff0000, v211
	v_pk_add_f32 v[62:63], v[62:63], v[168:169]
	v_pk_add_f32 v[64:65], v[64:65], v[176:177]
	v_lshlrev_b32_e32 v168, 16, v212
	v_and_b32_e32 v169, 0xffff0000, v212
	v_lshlrev_b32_e32 v176, 16, v213
	v_and_b32_e32 v177, 0xffff0000, v213
	v_pk_add_f32 v[58:59], v[58:59], v[168:169]
	v_pk_add_f32 v[60:61], v[60:61], v[176:177]
	v_cvt_pk_bf16_f32 v210, v62, v63
	v_cvt_pk_bf16_f32 v211, v64, v65
	v_cvt_pk_bf16_f32 v212, v58, v59
	v_cvt_pk_bf16_f32 v213, v60, v61
	global_store_dwordx4 v[248:249], v[210:213], off
	s_waitcnt vmcnt(15)
	v_lshlrev_b32_e32 v168, 16, v214
	v_and_b32_e32 v169, 0xffff0000, v214
	v_lshlrev_b32_e32 v176, 16, v215
	v_and_b32_e32 v177, 0xffff0000, v215
	v_pk_add_f32 v[54:55], v[54:55], v[168:169]
	v_pk_add_f32 v[56:57], v[56:57], v[176:177]
	v_lshlrev_b32_e32 v168, 16, v216
	v_and_b32_e32 v169, 0xffff0000, v216
	v_lshlrev_b32_e32 v176, 16, v217
	v_and_b32_e32 v177, 0xffff0000, v217
	v_pk_add_f32 v[50:51], v[50:51], v[168:169]
	v_pk_add_f32 v[52:53], v[52:53], v[176:177]
	v_cvt_pk_bf16_f32 v214, v54, v55
	v_cvt_pk_bf16_f32 v215, v56, v57
	v_cvt_pk_bf16_f32 v216, v50, v51
	v_cvt_pk_bf16_f32 v217, v52, v53
	global_store_dwordx4 v[248:249], v[214:217], off offset:256
	s_waitcnt vmcnt(15)
	v_lshlrev_b32_e32 v168, 16, v218
	v_and_b32_e32 v169, 0xffff0000, v218
	v_lshlrev_b32_e32 v176, 16, v219
	v_and_b32_e32 v177, 0xffff0000, v219
	v_pk_add_f32 v[46:47], v[46:47], v[168:169]
	v_pk_add_f32 v[48:49], v[48:49], v[176:177]
	v_lshlrev_b32_e32 v168, 16, v220
	v_and_b32_e32 v169, 0xffff0000, v220
	v_lshlrev_b32_e32 v176, 16, v221
	v_and_b32_e32 v177, 0xffff0000, v221
	v_pk_add_f32 v[42:43], v[42:43], v[168:169]
	v_pk_add_f32 v[44:45], v[44:45], v[176:177]
	v_cvt_pk_bf16_f32 v218, v46, v47
	v_cvt_pk_bf16_f32 v219, v48, v49
	v_cvt_pk_bf16_f32 v220, v42, v43
	v_cvt_pk_bf16_f32 v221, v44, v45
	global_store_dwordx4 v[250:251], v[218:221], off
	s_waitcnt vmcnt(15)
	v_lshlrev_b32_e32 v168, 16, v222
	v_and_b32_e32 v169, 0xffff0000, v222
	v_lshlrev_b32_e32 v176, 16, v223
	v_and_b32_e32 v177, 0xffff0000, v223
	v_pk_add_f32 v[38:39], v[38:39], v[168:169]
	v_pk_add_f32 v[40:41], v[40:41], v[176:177]
	v_lshlrev_b32_e32 v168, 16, v224
	v_and_b32_e32 v169, 0xffff0000, v224
	v_lshlrev_b32_e32 v176, 16, v225
	v_and_b32_e32 v177, 0xffff0000, v225
	v_pk_add_f32 v[34:35], v[34:35], v[168:169]
	v_pk_add_f32 v[36:37], v[36:37], v[176:177]
	v_cvt_pk_bf16_f32 v222, v38, v39
	v_cvt_pk_bf16_f32 v223, v40, v41
	v_cvt_pk_bf16_f32 v224, v34, v35
	v_cvt_pk_bf16_f32 v225, v36, v37
	global_store_dwordx4 v[250:251], v[222:225], off offset:256
	s_waitcnt vmcnt(15)
	v_lshlrev_b32_e32 v168, 16, v226
	v_and_b32_e32 v169, 0xffff0000, v226
	v_lshlrev_b32_e32 v176, 16, v227
	v_and_b32_e32 v177, 0xffff0000, v227
	v_pk_add_f32 v[30:31], v[30:31], v[168:169]
	v_pk_add_f32 v[32:33], v[32:33], v[176:177]
	v_lshlrev_b32_e32 v168, 16, v228
	v_and_b32_e32 v169, 0xffff0000, v228
	v_lshlrev_b32_e32 v176, 16, v229
	v_and_b32_e32 v177, 0xffff0000, v229
	v_pk_add_f32 v[26:27], v[26:27], v[168:169]
	v_pk_add_f32 v[28:29], v[28:29], v[176:177]
	v_cvt_pk_bf16_f32 v226, v30, v31
	v_cvt_pk_bf16_f32 v227, v32, v33
	v_cvt_pk_bf16_f32 v228, v26, v27
	v_cvt_pk_bf16_f32 v229, v28, v29
	global_store_dwordx4 v[252:253], v[226:229], off
	s_waitcnt vmcnt(15)
	v_lshlrev_b32_e32 v168, 16, v230
	v_and_b32_e32 v169, 0xffff0000, v230
	v_lshlrev_b32_e32 v176, 16, v231
	v_and_b32_e32 v177, 0xffff0000, v231
	v_pk_add_f32 v[22:23], v[22:23], v[168:169]
	v_pk_add_f32 v[24:25], v[24:25], v[176:177]
	v_lshlrev_b32_e32 v168, 16, v232
	v_and_b32_e32 v169, 0xffff0000, v232
	v_lshlrev_b32_e32 v176, 16, v233
	v_and_b32_e32 v177, 0xffff0000, v233
	v_pk_add_f32 v[18:19], v[18:19], v[168:169]
	v_pk_add_f32 v[20:21], v[20:21], v[176:177]
	v_cvt_pk_bf16_f32 v230, v22, v23
	v_cvt_pk_bf16_f32 v231, v24, v25
	v_cvt_pk_bf16_f32 v232, v18, v19
	v_cvt_pk_bf16_f32 v233, v20, v21
	global_store_dwordx4 v[252:253], v[230:233], off offset:256
	s_waitcnt vmcnt(15)
	v_lshlrev_b32_e32 v168, 16, v234
	v_and_b32_e32 v169, 0xffff0000, v234
	v_lshlrev_b32_e32 v176, 16, v235
	v_and_b32_e32 v177, 0xffff0000, v235
	v_pk_add_f32 v[14:15], v[14:15], v[168:169]
	v_pk_add_f32 v[16:17], v[16:17], v[176:177]
	v_lshlrev_b32_e32 v168, 16, v236
	v_and_b32_e32 v169, 0xffff0000, v236
	v_lshlrev_b32_e32 v176, 16, v237
	v_and_b32_e32 v177, 0xffff0000, v237
	v_pk_add_f32 v[10:11], v[10:11], v[168:169]
	v_pk_add_f32 v[12:13], v[12:13], v[176:177]
	v_cvt_pk_bf16_f32 v234, v14, v15
	v_cvt_pk_bf16_f32 v235, v16, v17
	v_cvt_pk_bf16_f32 v236, v10, v11
	v_cvt_pk_bf16_f32 v237, v12, v13
	global_store_dwordx4 v[174:175], v[234:237], off
	s_waitcnt vmcnt(15)
	v_lshlrev_b32_e32 v168, 16, v238
	v_and_b32_e32 v169, 0xffff0000, v238
	v_lshlrev_b32_e32 v176, 16, v239
	v_and_b32_e32 v177, 0xffff0000, v239
	v_pk_add_f32 v[6:7], v[6:7], v[168:169]
	v_pk_add_f32 v[8:9], v[8:9], v[176:177]
	v_lshlrev_b32_e32 v168, 16, v240
	v_and_b32_e32 v169, 0xffff0000, v240
	v_lshlrev_b32_e32 v176, 16, v241
	v_and_b32_e32 v177, 0xffff0000, v241
	v_pk_add_f32 v[2:3], v[2:3], v[168:169]
	v_pk_add_f32 v[4:5], v[4:5], v[176:177]
	v_cvt_pk_bf16_f32 v238, v6, v7
	v_cvt_pk_bf16_f32 v239, v8, v9
	v_cvt_pk_bf16_f32 v240, v2, v3
	v_cvt_pk_bf16_f32 v241, v4, v5
	global_store_dwordx4 v[174:175], v[238:241], off offset:256
	s_cbranch_vccz .LBB0_307

; __device__ void phase_seq(const KP& p, int l) {
;   for (int u = p.bid; u < 512; u += p.nblk) {
;     int uu = u & 255, soff = (u >= 256) ? 8 : 0;
;     if (uu < 128) ssd_seq(p, l, soff + (uu >> 4), (uu & 15) >> 1, uu & 1);
.LBB0_318:
	s_andn2_b64 vcc, exec, s[0:1]
	s_cbranch_vccnz .LBB0_408
	v_readlane_b32 s0, v255, 42
	s_cmpk_gt_i32 s0, 0x1ff
	s_cbranch_scc1 .LBB0_408
	s_lshl_b64 s[40:41], s[92:93], 5
	s_lshl_b64 s[46:47], s[92:93], 6
	v_readlane_b32 s0, v255, 45
	v_readlane_b32 s1, v255, 46
	s_add_u32 s50, s0, 0x1c441000
	s_addc_u32 s51, s1, 0
	s_add_u32 s78, s0, 0x4221000
	s_addc_u32 s79, s1, 0
	s_add_u32 s91, s0, 0x12a49000
	s_addc_u32 s90, s1, 0
	v_readlane_b32 s99, v255, 42
	v_readlane_b32 s0, v255, 43
	s_lshl_b32 s83, s0, 5
	v_readlane_b32 s1, v255, 44
	s_branch .LBB0_323

; __device__ void phase_seq(const KP& p, int l) {
;   for (int u = p.bid; u < 512; u += p.nblk) {
;     int uu = u & 255, soff = (u >= 256) ? 8 : 0;
;     if (uu < 128) ssd_seq(p, l, soff + (uu >> 4), (uu & 15) >> 1, uu & 1);
;     else { int v = uu - 128; gla_seq(p, l, soff + (v >> 4), (v & 15) >> 2, v & 3); }
.LBB0_322:
	v_readlane_b32 s0, v255, 43
	s_add_i32 s99, s99, s0
	s_cmpk_gt_i32 s99, 0x1ff
	s_waitcnt lgkmcnt(0)
	s_barrier
	v_readlane_b32 s1, v255, 44
	s_cbranch_scc1 .LBB0_408
.LBB0_323:
	s_and_b32 s84, s99, 0x180
	s_and_b32 s82, s99, 7
	s_lshl_b32 s82, s82, 4
	s_or_b32 s84, s84, s82
	s_bfe_u32 s82, s99, 0x40003
	s_or_b32 s84, s84, s82
	s_lshl_b32 s82, s84, 5
	s_and_b32 s14, s84, 0xff
	s_cmpk_gt_i32 s84, 0xff
	s_cselect_b32 s15, 8, 0
	s_cmpk_gt_u32 s14, 0x7f
	s_mov_b64 s[0:1], -1
	s_cbranch_scc0 .LBB0_381
	s_add_i32 s0, s14, 0xffffff80
	s_lshr_b32 s52, s0, 4
	s_add_i32 s52, s52, s15
	s_cmp_lt_u32 s52, 8
	s_cselect_b64 s[0:1], -1, 0
	s_cmp_gt_u32 s52, 7
	s_cselect_b64 s[76:77], -1, 0
	v_mov_b32_e32 v0, v156
	s_mov_b64 s[38:39], -1
	s_and_b64 vcc, exec, s[76:77]
	s_cbranch_vccz .LBB0_326
	s_lshl_b32 s2, s52, 6
	s_or_b32 s72, s2, 0x8200
	s_mov_b64 s[38:39], 0

; __device__ void gla_seq(const KP& p, int l, int s, int h, int vq) {
;     ...
;   const unsigned qoff = (unsigned)(((ti * 16 + fr) * NIN + 1536 + h * 128 + fq * 8) * 2);
;   const unsigned koff = (unsigned)((((kA >> 2)) * NIN + 2048 + h * 128 + (kA & 3) * 32 + fq * 8) * 2);
;   unsigned voff[2];
; #pragma unroll
;   for (int vt = 0; vt < 2; ++vt) { int _v = vq * 32 + vt * 16 + fr; voff[vt] = (unsigned)(((_v >> 2) * NIN + 2560 + h * 128 + (_v & 3) * 32 + fq * 8) * 2); }
;   const unsigned ooff = (unsigned)(((ti * 16 + fq * 4) * DM + oc) * 2);
;   const unsigned doff = (unsigned)((h * 128 + 16 * w + fq * 4) * 4);
;     ...
; #pragma unroll
;   for (int k = 0; k < 4; ++k) GLA_LOAD(k, min(k, nst - 1));
.LBB0_348:
	v_lshrrev_b32_e32 v3, 3, v0
	s_waitcnt vmcnt(0)
	v_cvt_pk_bf16_f32 v2, v25, s0
	v_and_b32_e32 v3, 16, v3
	ds_write_b16 v5, v2 offset:6
	v_or_b32_e32 v5, v3, v175
	s_lshl_b32 s56, s56, 7
	v_or_b32_e32 v2, v151, v175
	v_mul_u32_u24_e32 v5, 0xe00, v5
	v_lshlrev_b32_e32 v174, 3, v4
	v_or3_b32 v4, v5, s56, v174
	v_lshrrev_b32_e32 v2, 2, v2
	s_movk_i32 s58, 0xe00
	v_lshlrev_b32_e32 v0, 5, v0
	v_or_b32_e32 v5, s3, v175
	v_mul_lo_u32 v2, v2, s58
	v_and_b32_e32 v0, 0x60, v0
	v_lshrrev_b32_e32 v5, 2, v5
	v_or_b32_e32 v2, v2, v0
	v_mul_u32_u24_e32 v5, 0xe00, v5
	v_or_b32_e32 v0, s56, v0
	s_or_b32 s57, s3, s56
	v_and_b32_e32 v195, 16, v151
	v_or3_b32 v2, v2, s56, v174
	v_or3_b32 v0, v0, v174, v5
	v_lshl_add_u32 v150, v4, 1, v173
	v_mov_b32_e32 v4, 0x1000
	v_or_b32_e32 v141, v153, v3
	v_lshl_add_u32 v8, v0, 1, v165
	v_or3_b32 v0, s57, v175, v195
	v_lshl_add_u32 v152, v2, 1, v4
	v_lshlrev_b32_e32 v2, 11, v141
	v_readlane_b32 s16, v255, 45
	v_lshl_or_b32 v0, v0, 1, v2
	v_readlane_b32 s17, v255, 46
	v_add_u32_e32 v2, s56, v151
	s_add_i32 s3, s2, -1
	v_lshl_add_u64 v[4:5], s[16:17], 0, v[0:1]
	s_mov_b64 s[56:57], 0x12a29400
	s_mul_i32 s60, s72, 0x1c00
	v_or_b32_e32 v2, v2, v153
	v_lshl_add_u64 v[148:149], v[4:5], 0, s[56:57]
	s_mul_hi_u32 s57, s72, 0x1c00
	s_add_u32 s56, s36, s60
	v_lshlrev_b32_e32 v2, 2, v2
	v_mov_b32_e32 v3, v1
	s_addc_u32 s57, s37, s57
	s_lshl_b64 s[58:59], s[72:73], 11
	v_lshl_add_u64 v[154:155], s[50:51], 0, v[2:3]
	v_lshl_add_u64 v[2:3], v[148:149], 0, s[58:59]
	s_waitcnt lgkmcnt(0)
	s_barrier
	global_load_dwordx4 v[134:137], v150, s[56:57]
	global_load_dwordx4 v[130:133], v150, s[56:57] offset:64
	global_load_dwordx4 v[126:129], v150, s[56:57] offset:128
	global_load_dwordx4 v[122:125], v150, s[56:57] offset:192
	global_load_ushort v193, v[2:3], off
	global_load_ushort v192, v[2:3], off offset:2048
	v_add_co_u32_e32 v2, vcc, s62, v2
	v_mov_b32_e32 v0, v8
	s_nop 0
	v_addc_co_u32_e32 v3, vcc, 0, v3, vcc
	global_load_ushort v191, v[2:3], off
	global_load_ushort v190, v[2:3], off offset:2048
	global_load_dwordx4 v[90:93], v152, s[56:57]
	v_lshl_add_u64 v[2:3], s[56:57], 0, v[0:1]
	s_movk_i32 s63, 0x7000
	v_add_co_u32_e32 v2, vcc, s63, v2
	s_mov_b32 s75, s73
	s_nop 0
	v_addc_co_u32_e32 v3, vcc, 0, v3, vcc
	global_load_dwordx4 v[106:109], v8, s[56:57]
	global_load_dwordx4 v[94:97], v[2:3], off
	s_lshl_b64 s[56:57], s[74:75], 11
	v_lshl_add_u64 v[2:3], v[154:155], 0, s[56:57]
	s_add_i32 s56, s72, 32
	s_add_i32 s60, s60, 0x38000
	s_mov_b32 s57, s73
	s_mul_hi_u32 s59, s56, 0x1c00
	s_add_u32 s58, s36, s60
	s_addc_u32 s59, s37, s59
	s_lshl_b64 s[56:57], s[56:57], 11
	global_load_dwordx4 v[102:105], v[2:3], off
	v_lshl_add_u64 v[2:3], v[148:149], 0, s[56:57]
	global_load_ushort v247, v[148:149], off
	global_load_ushort v247, v[148:149], off
	global_load_ushort v247, v[148:149], off
	global_load_ushort v247, v[148:149], off
	global_load_dwordx4 v[118:121], v150, s[58:59]
	global_load_dwordx4 v[114:117], v150, s[58:59] offset:64
	global_load_dwordx4 v[110:113], v150, s[58:59] offset:128
	global_load_dwordx4 v[98:101], v150, s[58:59] offset:192
	global_load_ushort v189, v[2:3], off
	global_load_ushort v187, v[2:3], off offset:2048
	v_add_co_u32_e32 v2, vcc, s62, v2
	s_add_i32 s60, s74, 1
	s_nop 0
	v_addc_co_u32_e32 v3, vcc, 0, v3, vcc
	global_load_ushort v188, v[2:3], off
	global_load_ushort v186, v[2:3], off offset:2048
	global_load_dwordx4 v[58:61], v152, s[58:59]
	v_lshl_add_u64 v[2:3], s[58:59], 0, v[0:1]
	s_mov_b32 s61, s73
	v_add_co_u32_e32 v2, vcc, s63, v2
	s_lshl_b64 s[56:57], s[60:61], 11
	s_nop 0
	v_addc_co_u32_e32 v3, vcc, 0, v3, vcc
	s_min_u32 s60, s3, 2
	global_load_dwordx4 v[74:77], v8, s[58:59]
	global_load_dwordx4 v[62:65], v[2:3], off
	v_lshl_add_u64 v[2:3], v[154:155], 0, s[56:57]
	s_lshl_b32 s56, s60, 5
	s_add_i32 s56, s56, s72
	s_mul_i32 s58, s56, 0x1c00
	s_mov_b32 s57, s73
	s_mul_hi_u32 s59, s56, 0x1c00
	s_add_u32 s58, s36, s58
	s_addc_u32 s59, s37, s59
	s_lshl_b64 s[56:57], s[56:57], 11
	global_load_dwordx4 v[66:69], v[2:3], off
	v_lshl_add_u64 v[2:3], v[148:149], 0, s[56:57]
	global_load_ushort v247, v[148:149], off
	global_load_ushort v247, v[148:149], off
	global_load_ushort v247, v[148:149], off
	global_load_ushort v247, v[148:149], off
	global_load_dwordx4 v[86:89], v150, s[58:59]
	global_load_dwordx4 v[82:85], v150, s[58:59] offset:64
	global_load_dwordx4 v[78:81], v150, s[58:59] offset:128
	global_load_dwordx4 v[70:73], v150, s[58:59] offset:192
	global_load_ushort v185, v[2:3], off
	global_load_ushort v183, v[2:3], off offset:2048
	v_add_co_u32_e32 v2, vcc, s62, v2
	s_add_i32 s60, s74, s60
	s_nop 0
	v_addc_co_u32_e32 v3, vcc, 0, v3, vcc
	global_load_ushort v184, v[2:3], off
	global_load_ushort v182, v[2:3], off offset:2048
	global_load_dwordx4 v[30:33], v152, s[58:59]
	v_lshl_add_u64 v[2:3], s[58:59], 0, v[0:1]
	v_add_co_u32_e32 v2, vcc, s63, v2
	s_lshl_b64 s[56:57], s[60:61], 11
	s_nop 0
	v_addc_co_u32_e32 v3, vcc, 0, v3, vcc
	s_min_u32 s60, s3, 3
	global_load_dwordx4 v[54:57], v8, s[58:59]
	global_load_dwordx4 v[42:45], v[2:3], off
	v_lshl_add_u64 v[2:3], v[154:155], 0, s[56:57]
	s_lshl_b32 s56, s60, 5
	s_add_i32 s56, s56, s72
	s_mul_i32 s58, s56, 0x1c00
	s_mov_b32 s57, s73
	s_mul_hi_u32 s59, s56, 0x1c00
	s_add_u32 s58, s36, s58
	s_addc_u32 s59, s37, s59
	s_lshl_b64 s[56:57], s[56:57], 11
	global_load_dwordx4 v[50:53], v[2:3], off
	v_lshl_add_u64 v[2:3], v[148:149], 0, s[56:57]
	global_load_ushort v247, v[148:149], off
	global_load_ushort v247, v[148:149], off
	global_load_ushort v247, v[148:149], off
	global_load_ushort v247, v[148:149], off
	global_load_dwordx4 v[46:49], v150, s[58:59]
	global_load_dwordx4 v[38:41], v150, s[58:59] offset:64
	global_load_dwordx4 v[34:37], v150, s[58:59] offset:128
	global_load_dwordx4 v[26:29], v150, s[58:59] offset:192
	global_load_ushort v180, v[2:3], off
	global_load_ushort v178, v[2:3], off offset:2048
	v_add_co_u32_e32 v2, vcc, s62, v2
	s_add_i32 s60, s74, s60
	s_nop 0
	v_addc_co_u32_e32 v3, vcc, 0, v3, vcc
	v_lshl_add_u64 v[6:7], s[58:59], 0, v[0:1]
	v_add_co_u32_e32 v6, vcc, 0x7000, v6
	s_lshl_b64 s[56:57], s[60:61], 11
	global_load_ushort v179, v[2:3], off
	global_load_ushort v176, v[2:3], off offset:2048
	s_nop 0
	global_load_dwordx4 v[2:5], v152, s[58:59]
	v_addc_co_u32_e32 v7, vcc, 0, v7, vcc
	v_lshl_add_u64 v[14:15], v[154:155], 0, s[56:57]
	global_load_dwordx4 v[18:21], v8, s[58:59]
	s_movk_i32 s87, 0x7000
	global_load_dwordx4 v[6:9], v[6:7], off
	s_mov_b64 s[76:77], -1
	global_load_dwordx4 v[14:17], v[14:15], off
	s_and_b64 vcc, exec, s[38:39]
	v_mul_u32_u24_e32 v194, 0x110, v195
	s_cbranch_vccnz .LBB0_350
	v_mul_u32_u24_e32 v196, 0x110, v195
	s_mov_b64 s[76:77], 0

.Lgla_dummy_e:
	s_or_b64 exec, exec, s[76:77]
	global_load_ushort v247, v[148:149], off
	global_load_ushort v247, v[148:149], off
	global_load_ushort v247, v[148:149], off
	global_load_ushort v247, v[148:149], off
	s_branch .LBB0_354

; #define LBAR() do { asm volatile("s_waitcnt lgkmcnt(0)" ::: "memory"); __builtin_amdgcn_s_barrier(); asm volatile("" ::: "memory"); } while (0)
; #define LBAR() do { asm volatile("s_waitcnt lgkmcnt(0)" ::: "memory"); __builtin_amdgcn_s_barrier(); asm volatile("" ::: "memory"); } while (0)
; __device__ void gla_seq(const KP& p, int l, int s, int h, int vq) {
;     ...
; #pragma unroll
;   for (int k = 0; k < 4; ++k) GLA_LOAD(k, min(k, nst - 1));
;   int st0 = 0;
;   for (; st0 + 3 < nst; st0 += 4) {
; #pragma unroll
;     for (int k = 0; k < 4; ++k) {
;       const int st = st0 + k;
;       GLA_STEP(k, st);
;       GLA_LOAD(k, min(st + 4, nst - 1));
;       LBAR();
.LBB0_353:
	ds_read_b128 v[198:201], v195
	s_add_i32 s60, s72, s57
	s_ashr_i32 s61, s60, 31
	v_cmp_gt_u32_e32 vcc, s86, v197
	s_lshl_b64 s[60:61], s[60:61], 11
	s_waitcnt vmcnt(59) lgkmcnt(0)
	v_mfma_f32_16x16x32_bf16 v[134:137], v[134:137], v[198:201], 0
	ds_read_b128 v[198:201], v195 offset:64
	s_waitcnt vmcnt(58) lgkmcnt(0)
	v_mfma_f32_16x16x32_bf16 v[130:133], v[130:133], v[198:201], 0
	ds_read_b128 v[198:201], v195 offset:128
	s_waitcnt vmcnt(57) lgkmcnt(0)
	v_mfma_f32_16x16x32_bf16 v[126:129], v[126:129], v[198:201], v[134:137]
	s_nop 2
	ds_read_b128 v[134:137], v195 offset:192
	s_waitcnt vmcnt(56) lgkmcnt(0)
	v_mfma_f32_16x16x32_bf16 v[122:125], v[122:125], v[134:137], v[130:133]
	s_nop 7
	v_pk_add_f32 v[124:125], v[128:129], v[124:125]
	v_pk_add_f32 v[122:123], v[126:127], v[122:123]
	s_waitcnt vmcnt(55)
	v_lshlrev_b32_e32 v128, 16, v193
	v_add_f32_e32 v122, v122, v128
	v_cvt_pk_bf16_f32 v122, v122, s0
	v_cndmask_b32_sdwa v122, v1, v122, vcc dst_sel:DWORD dst_unused:UNUSED_PAD src0_sel:DWORD src1_sel:WORD_0
	v_lshl_add_u64 v[126:127], v[148:149], 0, s[60:61]
	global_store_short v[126:127], v122, off
	s_waitcnt vmcnt(55)
	v_lshlrev_b32_e32 v122, 16, v192
	v_add_f32_e32 v128, v123, v122
	v_add_u32_e32 v122, 1, v197
	s_mov_b64 s[60:61], 0x800
	v_cmp_gt_u32_e32 vcc, s86, v122
	v_lshl_add_u64 v[122:123], v[126:127], 0, s[60:61]
	v_cvt_pk_bf16_f32 v128, v128, s0
	v_cndmask_b32_sdwa v128, v1, v128, vcc dst_sel:DWORD dst_unused:UNUSED_PAD src0_sel:DWORD src1_sel:WORD_0
	global_store_short v[122:123], v128, off
	s_waitcnt vmcnt(55)
	v_lshlrev_b32_e32 v122, 16, v191
	v_add_f32_e32 v124, v124, v122
	v_add_u32_e32 v122, 2, v197
	s_mov_b64 s[60:61], 0x1000
	v_cmp_gt_u32_e32 vcc, s86, v122
	v_lshl_add_u64 v[122:123], v[126:127], 0, s[60:61]
	v_cvt_pk_bf16_f32 v124, v124, s0
	v_cndmask_b32_sdwa v124, v1, v124, vcc dst_sel:DWORD dst_unused:UNUSED_PAD src0_sel:DWORD src1_sel:WORD_0
	global_store_short v[122:123], v124, off
	s_waitcnt vmcnt(55)
	v_lshlrev_b32_e32 v122, 16, v190
	v_add_f32_e32 v124, v125, v122
	v_add_u32_e32 v122, 3, v197
	v_cmp_gt_u32_e32 vcc, s86, v122
	s_mov_b64 s[60:61], 0x1800
	v_cvt_pk_bf16_f32 v124, v124, s0
	v_lshl_add_u64 v[122:123], v[126:127], 0, s[60:61]
	v_cndmask_b32_sdwa v124, v1, v124, vcc dst_sel:DWORD dst_unused:UNUSED_PAD src0_sel:DWORD src1_sel:WORD_0
	global_store_short v[122:123], v124, off
.LBB0_354:
	s_or_b64 exec, exec, s[76:77]
	s_add_i32 s56, s58, -3
	s_min_i32 s59, s56, s3
	s_lshl_b32 s60, s59, 5
	s_add_i32 s60, s60, s72
	s_ashr_i32 s61, s60, 31
	s_mul_i32 s62, s60, 0x1c00
	s_mul_hi_i32 s63, s60, 0x1c00
	s_add_u32 s62, s36, s62
	s_waitcnt vmcnt(52)
	v_pk_mul_f32 v[12:13], v[104:105], v[12:13]
	v_pk_mul_f32 v[10:11], v[102:103], v[10:11]
	v_pk_mul_f32 v[24:25], v[104:105], v[24:25]
	v_pk_mul_f32 v[22:23], v[102:103], v[22:23]
	s_addc_u32 s63, s37, s63
	v_mfma_f32_16x16x32_bf16 v[10:13], v[90:93], v[106:109], v[10:13]
	s_lshl_b64 s[60:61], s[60:61], 11
	s_add_i32 s64, s59, s74
	s_ashr_i32 s65, s64, 31
	v_mfma_f32_16x16x32_bf16 v[22:25], v[90:93], v[94:97], v[22:25]
	v_lshl_add_u64 v[90:91], s[62:63], 0, v[150:151]
	global_load_dwordx4 v[134:137], v[90:91], off
	global_load_dwordx4 v[130:133], v[90:91], off offset:64
	global_load_dwordx4 v[126:129], v[90:91], off offset:128
	global_load_dwordx4 v[122:125], v[90:91], off offset:192
	v_lshl_add_u64 v[90:91], v[148:149], 0, s[60:61]
	v_add_co_u32_e32 v92, vcc, s75, v90
	v_lshl_add_u64 v[94:95], s[62:63], 0, v[0:1]
	s_nop 0
	v_addc_co_u32_e32 v93, vcc, 0, v91, vcc
	global_load_ushort v193, v[90:91], off
	global_load_ushort v192, v[90:91], off offset:2048
	global_load_ushort v191, v[92:93], off
	global_load_ushort v190, v[92:93], off offset:2048
	v_lshl_add_u64 v[90:91], s[62:63], 0, v[152:153]
	global_load_dwordx4 v[90:93], v[90:91], off
	s_nop 0
	global_load_dwordx4 v[106:109], v[94:95], off
	v_add_co_u32_e32 v94, vcc, 0x7000, v94
	s_lshl_b64 s[60:61], s[64:65], 11
	s_nop 0
	v_addc_co_u32_e32 v95, vcc, 0, v95, vcc
	v_lshl_add_u64 v[102:103], v[154:155], 0, s[60:61]
	global_load_dwordx4 v[94:97], v[94:95], off
	v_cvt_pk_bf16_f32 v167, v12, v13
	global_load_dwordx4 v[102:105], v[102:103], off
	v_cvt_pk_bf16_f32 v166, v10, v11
	ds_write_b64 v196, v[166:167] offset:8704
	v_cvt_pk_bf16_f32 v167, v24, v25
	v_cvt_pk_bf16_f32 v166, v22, v23
	ds_write_b64 v196, v[166:167] offset:13056
	s_waitcnt lgkmcnt(0)
	s_barrier
	s_and_saveexec_b64 s[76:77], s[38:39]
	s_cbranch_execz .Lgla_dummy_a
	ds_read_b128 v[198:201], v195 offset:8704
	s_add_i32 s59, s72, s57
	s_add_i32 s60, s59, 32
	s_ashr_i32 s61, s60, 31
	s_lshl_b64 s[60:61], s[60:61], 11
	s_waitcnt vmcnt(59) lgkmcnt(0)
	v_mfma_f32_16x16x32_bf16 v[118:121], v[118:121], v[198:201], 0
	ds_read_b128 v[198:201], v195 offset:8768
	s_waitcnt vmcnt(58) lgkmcnt(0)
	v_mfma_f32_16x16x32_bf16 v[114:117], v[114:117], v[198:201], 0
	ds_read_b128 v[198:201], v195 offset:8832
	s_waitcnt vmcnt(57) lgkmcnt(0)
	v_mfma_f32_16x16x32_bf16 v[110:113], v[110:113], v[198:201], v[118:121]
	s_nop 2
	ds_read_b128 v[118:121], v195 offset:8896
	s_waitcnt vmcnt(56) lgkmcnt(0)
	v_mfma_f32_16x16x32_bf16 v[98:101], v[98:101], v[118:121], v[114:117]
	s_nop 7
	v_pk_add_f32 v[100:101], v[112:113], v[100:101]
	v_pk_add_f32 v[98:99], v[110:111], v[98:99]
	s_waitcnt vmcnt(55)
	v_lshlrev_b32_e32 v113, 16, v189
	v_add_u32_e32 v112, 32, v197
	v_add_f32_e32 v98, v98, v113
	v_cmp_gt_u32_e32 vcc, s86, v112
	v_cvt_pk_bf16_f32 v98, v98, s0
	v_lshl_add_u64 v[110:111], v[148:149], 0, s[60:61]
	v_cndmask_b32_sdwa v98, v1, v98, vcc dst_sel:DWORD dst_unused:UNUSED_PAD src0_sel:DWORD src1_sel:WORD_0
	global_store_short v[110:111], v98, off
	s_waitcnt vmcnt(55)
	v_lshlrev_b32_e32 v98, 16, v187
	v_add_f32_e32 v112, v99, v98
	v_add_u32_e32 v98, 33, v197
	s_mov_b64 s[60:61], 0x800
	v_cmp_gt_u32_e32 vcc, s86, v98
	v_lshl_add_u64 v[98:99], v[110:111], 0, s[60:61]
	v_cvt_pk_bf16_f32 v112, v112, s0
	v_cndmask_b32_sdwa v112, v1, v112, vcc dst_sel:DWORD dst_unused:UNUSED_PAD src0_sel:DWORD src1_sel:WORD_0
	global_store_short v[98:99], v112, off
	s_waitcnt vmcnt(55)
	v_lshlrev_b32_e32 v98, 16, v188
	v_add_f32_e32 v100, v100, v98
	v_add_u32_e32 v98, 34, v197
	s_mov_b64 s[60:61], 0x1000
	v_cmp_gt_u32_e32 vcc, s86, v98
	v_lshl_add_u64 v[98:99], v[110:111], 0, s[60:61]
	v_cvt_pk_bf16_f32 v100, v100, s0
	v_cndmask_b32_sdwa v100, v1, v100, vcc dst_sel:DWORD dst_unused:UNUSED_PAD src0_sel:DWORD src1_sel:WORD_0
	global_store_short v[98:99], v100, off
	s_waitcnt vmcnt(55)
	v_lshlrev_b32_e32 v98, 16, v186
	v_add_f32_e32 v100, v101, v98
	v_add_u32_e32 v98, 35, v197
	v_cmp_gt_u32_e32 vcc, s86, v98
	s_mov_b64 s[60:61], 0x1800
	v_cvt_pk_bf16_f32 v100, v100, s0
	v_lshl_add_u64 v[98:99], v[110:111], 0, s[60:61]
	v_cndmask_b32_sdwa v100, v1, v100, vcc dst_sel:DWORD dst_unused:UNUSED_PAD src0_sel:DWORD src1_sel:WORD_0
	global_store_short v[98:99], v100, off
	s_branch .LBB0_356
; __device__ void gla_seq(const KP& p, int l, int s, int h, int vq) {
;     ...
; #pragma unroll
;   for (int k = 0; k < 4; ++k) GLA_LOAD(k, min(k, nst - 1));
;   int st0 = 0;
;   for (; st0 + 3 < nst; st0 += 4) {
; #pragma unroll
;     for (int k = 0; k < 4; ++k) {
;       const int st = st0 + k;
;       GLA_STEP(k, st);
;       GLA_LOAD(k, min(st + 4, nst - 1));
.Lgla_dummy_a:
	s_or_b64 exec, exec, s[76:77]
	global_load_ushort v247, v[148:149], off
	global_load_ushort v247, v[148:149], off
	global_load_ushort v247, v[148:149], off
	global_load_ushort v247, v[148:149], off
.LBB0_356:
	s_or_b64 exec, exec, s[76:77]
	s_add_i32 s59, s58, -2
	s_min_i32 s59, s59, s3
	s_lshl_b32 s60, s59, 5
	s_add_i32 s60, s60, s72
	s_ashr_i32 s61, s60, 31
	s_mul_i32 s62, s60, 0x1c00
	s_mul_hi_i32 s63, s60, 0x1c00
	s_add_u32 s62, s36, s62
	s_waitcnt vmcnt(52)
	v_pk_mul_f32 v[12:13], v[68:69], v[12:13]
	v_pk_mul_f32 v[10:11], v[66:67], v[10:11]
	v_pk_mul_f32 v[24:25], v[68:69], v[24:25]
	v_pk_mul_f32 v[22:23], v[66:67], v[22:23]
	s_addc_u32 s63, s37, s63
	v_mfma_f32_16x16x32_bf16 v[10:13], v[58:61], v[74:77], v[10:13]
	s_lshl_b64 s[60:61], s[60:61], 11
	s_add_i32 s64, s59, s74
	s_ashr_i32 s65, s64, 31
	v_mfma_f32_16x16x32_bf16 v[22:25], v[58:61], v[62:65], v[22:25]
	v_lshl_add_u64 v[58:59], s[62:63], 0, v[150:151]
	global_load_dwordx4 v[118:121], v[58:59], off
	global_load_dwordx4 v[114:117], v[58:59], off offset:64
	global_load_dwordx4 v[110:113], v[58:59], off offset:128
	global_load_dwordx4 v[98:101], v[58:59], off offset:192
	v_lshl_add_u64 v[58:59], v[148:149], 0, s[60:61]
	v_add_co_u32_e32 v60, vcc, s75, v58
	v_lshl_add_u64 v[62:63], s[62:63], 0, v[0:1]
	s_nop 0
	v_addc_co_u32_e32 v61, vcc, 0, v59, vcc
	global_load_ushort v189, v[58:59], off
	global_load_ushort v187, v[58:59], off offset:2048
	global_load_ushort v188, v[60:61], off
	global_load_ushort v186, v[60:61], off offset:2048
	v_lshl_add_u64 v[58:59], s[62:63], 0, v[152:153]
	global_load_dwordx4 v[58:61], v[58:59], off
	s_nop 0
	global_load_dwordx4 v[74:77], v[62:63], off
	v_add_co_u32_e32 v62, vcc, 0x7000, v62
	s_lshl_b64 s[60:61], s[64:65], 11
	s_nop 0
	v_addc_co_u32_e32 v63, vcc, 0, v63, vcc
	v_lshl_add_u64 v[66:67], v[154:155], 0, s[60:61]
	global_load_dwordx4 v[62:65], v[62:63], off
	v_cvt_pk_bf16_f32 v167, v12, v13
	global_load_dwordx4 v[66:69], v[66:67], off
	v_cvt_pk_bf16_f32 v166, v10, v11
	ds_write_b64 v196, v[166:167]
	v_cvt_pk_bf16_f32 v167, v24, v25
	v_cvt_pk_bf16_f32 v166, v22, v23
	ds_write_b64 v196, v[166:167] offset:4352
	s_waitcnt lgkmcnt(0)
	s_barrier
	s_and_saveexec_b64 s[76:77], s[38:39]
	s_cbranch_execz .Lgla_dummy_b
	ds_read_b128 v[198:201], v195
	s_add_i32 s59, s72, s57
	s_add_i32 s60, s59, 64
	s_ashr_i32 s61, s60, 31
	s_lshl_b64 s[60:61], s[60:61], 11
	s_waitcnt vmcnt(59) lgkmcnt(0)
	v_mfma_f32_16x16x32_bf16 v[86:89], v[86:89], v[198:201], 0
	ds_read_b128 v[198:201], v195 offset:64
	s_waitcnt vmcnt(58) lgkmcnt(0)
	v_mfma_f32_16x16x32_bf16 v[82:85], v[82:85], v[198:201], 0
	ds_read_b128 v[198:201], v195 offset:128
	s_waitcnt vmcnt(57) lgkmcnt(0)
	v_mfma_f32_16x16x32_bf16 v[78:81], v[78:81], v[198:201], v[86:89]
	s_nop 2
	ds_read_b128 v[86:89], v195 offset:192
	s_waitcnt vmcnt(56) lgkmcnt(0)
	v_mfma_f32_16x16x32_bf16 v[70:73], v[70:73], v[86:89], v[82:85]
	s_nop 7
	v_pk_add_f32 v[72:73], v[80:81], v[72:73]
	v_pk_add_f32 v[70:71], v[78:79], v[70:71]
	s_waitcnt vmcnt(55)
	v_lshlrev_b32_e32 v81, 16, v185
	v_add_u32_e32 v80, 64, v197
	v_add_f32_e32 v70, v70, v81
	v_cmp_gt_u32_e32 vcc, s86, v80
	v_cvt_pk_bf16_f32 v70, v70, s0
	v_lshl_add_u64 v[78:79], v[148:149], 0, s[60:61]
	v_cndmask_b32_sdwa v70, v1, v70, vcc dst_sel:DWORD dst_unused:UNUSED_PAD src0_sel:DWORD src1_sel:WORD_0
	global_store_short v[78:79], v70, off
	s_waitcnt vmcnt(55)
	v_lshlrev_b32_e32 v70, 16, v183
	v_add_f32_e32 v80, v71, v70
	v_add_u32_e32 v70, 0x41, v197
	s_mov_b64 s[60:61], 0x800
	v_cmp_gt_u32_e32 vcc, s86, v70
	v_lshl_add_u64 v[70:71], v[78:79], 0, s[60:61]
	v_cvt_pk_bf16_f32 v80, v80, s0
	v_cndmask_b32_sdwa v80, v1, v80, vcc dst_sel:DWORD dst_unused:UNUSED_PAD src0_sel:DWORD src1_sel:WORD_0
	global_store_short v[70:71], v80, off
	s_waitcnt vmcnt(55)
	v_lshlrev_b32_e32 v70, 16, v184
	v_add_f32_e32 v72, v72, v70
	v_add_u32_e32 v70, 0x42, v197
	s_mov_b64 s[60:61], 0x1000
	v_cmp_gt_u32_e32 vcc, s86, v70
	v_lshl_add_u64 v[70:71], v[78:79], 0, s[60:61]
	v_cvt_pk_bf16_f32 v72, v72, s0
	v_cndmask_b32_sdwa v72, v1, v72, vcc dst_sel:DWORD dst_unused:UNUSED_PAD src0_sel:DWORD src1_sel:WORD_0
	global_store_short v[70:71], v72, off
	s_waitcnt vmcnt(55)
	v_lshlrev_b32_e32 v70, 16, v182
	v_add_f32_e32 v72, v73, v70
	v_add_u32_e32 v70, 0x43, v197
	v_cmp_gt_u32_e32 vcc, s86, v70
	s_mov_b64 s[60:61], 0x1800
	v_cvt_pk_bf16_f32 v72, v72, s0
	v_lshl_add_u64 v[70:71], v[78:79], 0, s[60:61]
	v_cndmask_b32_sdwa v72, v1, v72, vcc dst_sel:DWORD dst_unused:UNUSED_PAD src0_sel:DWORD src1_sel:WORD_0
	global_store_short v[70:71], v72, off
	s_branch .LBB0_358

; __device__ void gla_seq(const KP& p, int l, int s, int h, int vq) {
;     ...
; #pragma unroll
;   for (int k = 0; k < 4; ++k) GLA_LOAD(k, min(k, nst - 1));
;   int st0 = 0;
;   for (; st0 + 3 < nst; st0 += 4) {
; #pragma unroll
;     for (int k = 0; k < 4; ++k) {
;       const int st = st0 + k;
;       GLA_STEP(k, st);
;       GLA_LOAD(k, min(st + 4, nst - 1));
.LBB0_358:
	s_or_b64 exec, exec, s[76:77]
	s_add_i32 s59, s58, -1
	s_min_i32 s59, s59, s3
	s_lshl_b32 s60, s59, 5
	s_add_i32 s60, s60, s72
	s_ashr_i32 s61, s60, 31
	s_mul_i32 s62, s60, 0x1c00
	s_mul_hi_i32 s63, s60, 0x1c00
	s_add_u32 s62, s36, s62
	s_waitcnt vmcnt(52)
	v_pk_mul_f32 v[12:13], v[52:53], v[12:13]
	v_pk_mul_f32 v[10:11], v[50:51], v[10:11]
	v_pk_mul_f32 v[24:25], v[52:53], v[24:25]
	v_pk_mul_f32 v[22:23], v[50:51], v[22:23]
	s_addc_u32 s63, s37, s63
	v_mfma_f32_16x16x32_bf16 v[10:13], v[30:33], v[54:57], v[10:13]
	s_lshl_b64 s[60:61], s[60:61], 11
	s_add_i32 s64, s59, s74
	s_ashr_i32 s65, s64, 31
	v_mfma_f32_16x16x32_bf16 v[22:25], v[30:33], v[42:45], v[22:25]
	v_lshl_add_u64 v[30:31], s[62:63], 0, v[150:151]
	global_load_dwordx4 v[86:89], v[30:31], off
	global_load_dwordx4 v[82:85], v[30:31], off offset:64
	global_load_dwordx4 v[78:81], v[30:31], off offset:128
	global_load_dwordx4 v[70:73], v[30:31], off offset:192
	v_lshl_add_u64 v[30:31], v[148:149], 0, s[60:61]
	v_add_co_u32_e32 v32, vcc, s75, v30
	v_lshl_add_u64 v[42:43], s[62:63], 0, v[0:1]
	s_nop 0
	v_addc_co_u32_e32 v33, vcc, 0, v31, vcc
	global_load_ushort v185, v[30:31], off
	global_load_ushort v183, v[30:31], off offset:2048
	global_load_ushort v184, v[32:33], off
	global_load_ushort v182, v[32:33], off offset:2048
	v_lshl_add_u64 v[30:31], s[62:63], 0, v[152:153]
	global_load_dwordx4 v[30:33], v[30:31], off
	s_nop 0
	global_load_dwordx4 v[54:57], v[42:43], off
	v_add_co_u32_e32 v42, vcc, 0x7000, v42
	s_lshl_b64 s[60:61], s[64:65], 11
	s_nop 0
	v_addc_co_u32_e32 v43, vcc, 0, v43, vcc
	v_lshl_add_u64 v[50:51], v[154:155], 0, s[60:61]
	global_load_dwordx4 v[42:45], v[42:43], off
	v_cvt_pk_bf16_f32 v167, v12, v13
	global_load_dwordx4 v[50:53], v[50:51], off
	v_cvt_pk_bf16_f32 v166, v10, v11
	ds_write_b64 v196, v[166:167] offset:8704
	v_cvt_pk_bf16_f32 v167, v24, v25
	v_cvt_pk_bf16_f32 v166, v22, v23
	ds_write_b64 v196, v[166:167] offset:13056
	s_waitcnt lgkmcnt(0)
	s_barrier
	s_and_saveexec_b64 s[76:77], s[38:39]
	s_cbranch_execz .Lgla_dummy_c
	ds_read_b128 v[198:201], v195 offset:8704
	s_add_i32 s59, s72, s57
	s_add_i32 s60, s59, 0x60
	s_ashr_i32 s61, s60, 31
	s_lshl_b64 s[60:61], s[60:61], 11
	s_waitcnt vmcnt(59) lgkmcnt(0)
	v_mfma_f32_16x16x32_bf16 v[46:49], v[46:49], v[198:201], 0
	ds_read_b128 v[198:201], v195 offset:8768
	s_waitcnt vmcnt(58) lgkmcnt(0)
	v_mfma_f32_16x16x32_bf16 v[38:41], v[38:41], v[198:201], 0
	ds_read_b128 v[198:201], v195 offset:8832
	s_waitcnt vmcnt(57) lgkmcnt(0)
	v_mfma_f32_16x16x32_bf16 v[34:37], v[34:37], v[198:201], v[46:49]
	s_nop 2
	ds_read_b128 v[46:49], v195 offset:8896
	s_waitcnt vmcnt(56) lgkmcnt(0)
	v_mfma_f32_16x16x32_bf16 v[26:29], v[26:29], v[46:49], v[38:41]
	s_nop 7
	v_pk_add_f32 v[28:29], v[36:37], v[28:29]
	v_pk_add_f32 v[26:27], v[34:35], v[26:27]
	s_waitcnt vmcnt(55)
	v_lshlrev_b32_e32 v37, 16, v180
	v_add_u32_e32 v36, 0x60, v197
	v_add_f32_e32 v26, v26, v37
	v_cmp_gt_u32_e32 vcc, s86, v36
	v_cvt_pk_bf16_f32 v26, v26, s0
	v_lshl_add_u64 v[34:35], v[148:149], 0, s[60:61]
	v_cndmask_b32_sdwa v26, v1, v26, vcc dst_sel:DWORD dst_unused:UNUSED_PAD src0_sel:DWORD src1_sel:WORD_0
	global_store_short v[34:35], v26, off
	s_waitcnt vmcnt(55)
	v_lshlrev_b32_e32 v26, 16, v178
	v_add_f32_e32 v36, v27, v26
	v_add_u32_e32 v26, 0x61, v197
	s_mov_b64 s[60:61], 0x800
	v_cmp_gt_u32_e32 vcc, s86, v26
	v_lshl_add_u64 v[26:27], v[34:35], 0, s[60:61]
	v_cvt_pk_bf16_f32 v36, v36, s0
	v_cndmask_b32_sdwa v36, v1, v36, vcc dst_sel:DWORD dst_unused:UNUSED_PAD src0_sel:DWORD src1_sel:WORD_0
	global_store_short v[26:27], v36, off
	s_waitcnt vmcnt(55)
	v_lshlrev_b32_e32 v26, 16, v179
	v_add_f32_e32 v28, v28, v26
	v_add_u32_e32 v26, 0x62, v197
	s_mov_b64 s[60:61], 0x1000
	v_cmp_gt_u32_e32 vcc, s86, v26
	v_lshl_add_u64 v[26:27], v[34:35], 0, s[60:61]
	v_cvt_pk_bf16_f32 v28, v28, s0
	v_cndmask_b32_sdwa v28, v1, v28, vcc dst_sel:DWORD dst_unused:UNUSED_PAD src0_sel:DWORD src1_sel:WORD_0
	global_store_short v[26:27], v28, off
	s_waitcnt vmcnt(55)
	v_lshlrev_b32_e32 v26, 16, v176
	v_add_f32_e32 v28, v29, v26
	v_add_u32_e32 v26, 0x63, v197
	v_cmp_gt_u32_e32 vcc, s86, v26
	s_mov_b64 s[60:61], 0x1800
	v_cvt_pk_bf16_f32 v28, v28, s0
	v_lshl_add_u64 v[26:27], v[34:35], 0, s[60:61]
	v_cndmask_b32_sdwa v28, v1, v28, vcc dst_sel:DWORD dst_unused:UNUSED_PAD src0_sel:DWORD src1_sel:WORD_0
	global_store_short v[26:27], v28, off
	s_branch .LBB0_360

; #define LBAR() do { asm volatile("s_waitcnt lgkmcnt(0)" ::: "memory"); __builtin_amdgcn_s_barrier(); asm volatile("" ::: "memory"); } while (0)
; #define LBAR() do { asm volatile("s_waitcnt lgkmcnt(0)" ::: "memory"); __builtin_amdgcn_s_barrier(); asm volatile("" ::: "memory"); } while (0)
; __device__ void gla_seq(const KP& p, int l, int s, int h, int vq) {
;     ...
; #pragma unroll
;   for (int k = 0; k < 4; ++k) GLA_LOAD(k, min(k, nst - 1));
;   int st0 = 0;
;   for (; st0 + 3 < nst; st0 += 4) {
; #pragma unroll
;     for (int k = 0; k < 4; ++k) {
;       const int st = st0 + k;
;       GLA_STEP(k, st);
;       GLA_LOAD(k, min(st + 4, nst - 1));
;       LBAR();
;     }
.LBB0_360:
	s_or_b64 exec, exec, s[76:77]
	s_min_i32 s59, s58, s3
	s_lshl_b32 s60, s59, 5
	s_add_i32 s60, s60, s72
	s_ashr_i32 s61, s60, 31
	s_mul_i32 s62, s60, 0x1c00
	s_mul_hi_i32 s63, s60, 0x1c00
	s_add_u32 s62, s36, s62
	s_waitcnt vmcnt(52)
	v_pk_mul_f32 v[12:13], v[16:17], v[12:13]
	v_pk_mul_f32 v[10:11], v[14:15], v[10:11]
	v_pk_mul_f32 v[16:17], v[16:17], v[24:25]
	v_pk_mul_f32 v[14:15], v[14:15], v[22:23]
	s_addc_u32 s63, s37, s63
	v_mfma_f32_16x16x32_bf16 v[10:13], v[2:5], v[18:21], v[10:13]
	s_lshl_b64 s[60:61], s[60:61], 11
	s_add_i32 s64, s59, s74
	s_ashr_i32 s65, s64, 31
	v_mfma_f32_16x16x32_bf16 v[22:25], v[2:5], v[6:9], v[14:17]
	v_lshl_add_u64 v[2:3], s[62:63], 0, v[150:151]
	global_load_dwordx4 v[46:49], v[2:3], off
	global_load_dwordx4 v[38:41], v[2:3], off offset:64
	global_load_dwordx4 v[34:37], v[2:3], off offset:128
	global_load_dwordx4 v[26:29], v[2:3], off offset:192
	v_lshl_add_u64 v[2:3], v[148:149], 0, s[60:61]
	v_add_co_u32_e32 v4, vcc, s75, v2
	v_lshl_add_u64 v[6:7], s[62:63], 0, v[0:1]
	s_nop 0
	v_addc_co_u32_e32 v5, vcc, 0, v3, vcc
	global_load_ushort v180, v[2:3], off
	global_load_ushort v178, v[2:3], off offset:2048
	global_load_ushort v179, v[4:5], off
	global_load_ushort v176, v[4:5], off offset:2048
	v_lshl_add_u64 v[2:3], s[62:63], 0, v[152:153]
	global_load_dwordx4 v[2:5], v[2:3], off
	s_nop 0
	global_load_dwordx4 v[18:21], v[6:7], off
	v_add_co_u32_e32 v6, vcc, s87, v6
	s_lshl_b64 s[60:61], s[64:65], 11
	s_nop 0
	v_addc_co_u32_e32 v7, vcc, 0, v7, vcc
	v_lshl_add_u64 v[14:15], v[154:155], 0, s[60:61]
	global_load_dwordx4 v[6:9], v[6:7], off
	v_cvt_pk_bf16_f32 v167, v12, v13
	global_load_dwordx4 v[14:17], v[14:15], off
	v_cvt_pk_bf16_f32 v166, v10, v11
	ds_write_b64 v196, v[166:167]
	v_cvt_pk_bf16_f32 v167, v24, v25
	v_cvt_pk_bf16_f32 v166, v22, v23
	ds_write_b64 v196, v[166:167] offset:4352
	s_waitcnt lgkmcnt(0)
	s_barrier
	s_addk_i32 s57, 0x80
	s_add_i32 s59, s58, 4
	s_cmp_ge_u32 s58, s2
	s_cbranch_scc0 .LBB0_352
	s_movk_i32 s62, 0x1000
	v_cmp_gt_i32_e64 s[38:39], 4, v181
	s_cmp_lt_u32 s56, s2
	v_add3_u32 v0, 0, v194, v175
	s_cbranch_scc1 .LBB0_369

; __device__ __forceinline__ unsigned pack2(float a, float b) { f32v2_t v = {a, b}; bf16v2_t r = __builtin_convertvector(v, bf16v2_t); return __builtin_bit_cast(unsigned, r); }
; template <int EPI, int N, int K>
; __device__ __forceinline__ void gemm_phase(const KP& p, int l, const bfr* A, const bfr* Bt) {
;     ...
;     } else if (EPI == 2) {
;       bfr* hb = (bfr*)(p.ws + OFF_HB);
; #pragma unroll
;       for (int ai = 0; ai < 2; ++ai)
; #pragma unroll
;         for (int m = 0; m < 4; ++m) {
;           int row = erow + ai * HM + wr * 64 + m * 16 + fr;
; #pragma unroll
;           for (int bj = 0; bj < 2; ++bj) {
;             u32x4* hp = (u32x4*)(hb + (size_t)row * DM + ecol + bj * HALF + wc * 32 + fq * 8);
;             u32x4 h = *hp, o;
; #pragma unroll
;             for (int q2 = 0; q2 < 4; ++q2) {
;               f32v2_t hv2 = {__uint_as_float(h[q2] << 16), __uint_as_float(h[q2] & 0xffff0000u)};
;               f32v2_t av2 = {acc[ai][bj][m][q2 >> 1][(q2 & 1) * 2], acc[ai][bj][m][q2 >> 1][(q2 & 1) * 2 + 1]};
;               f32v2_t s2 = hv2 + av2;
;               o[q2] = pack2(s2.x, s2.y);
;             }
;             *hp = o;
;           }
;         }
.LBB0_1114:
	v_add_u32_e32 v134, s2, v147
	v_ashrrev_i32_e32 v135, 31, v134
	v_lshl_add_u64 v[132:133], s[42:43], 1, v[130:131]
	v_lshlrev_b64 v[166:167], 11, v[134:135]
	v_lshl_add_u64 v[166:167], v[132:133], 0, v[166:167]
	s_andn2_b64 vcc, exec, s[0:1]
	s_mov_b32 s2, s14
	s_mov_b64 s[98:99], 0x8000
	s_mov_b64 s[100:101], 0x28000
	v_lshl_add_u64 v[242:243], v[166:167], 0, s[98:99]
	v_lshl_add_u64 v[244:245], v[242:243], 0, s[98:99]
	v_lshl_add_u64 v[246:247], v[244:245], 0, s[98:99]
	v_lshl_add_u64 v[248:249], v[246:247], 0, s[100:101]
	v_lshl_add_u64 v[250:251], v[248:249], 0, s[98:99]
	v_lshl_add_u64 v[252:253], v[250:251], 0, s[98:99]
	v_lshl_add_u64 v[174:175], v[252:253], 0, s[98:99]
	global_load_dwordx4 v[178:181], v[166:167], off
	global_load_dwordx4 v[182:185], v[166:167], off offset:256
	global_load_dwordx4 v[186:189], v[242:243], off
	global_load_dwordx4 v[190:193], v[242:243], off offset:256
	global_load_dwordx4 v[194:197], v[244:245], off
	global_load_dwordx4 v[198:201], v[244:245], off offset:256
	global_load_dwordx4 v[202:205], v[246:247], off
	global_load_dwordx4 v[206:209], v[246:247], off offset:256
	global_load_dwordx4 v[210:213], v[248:249], off
	global_load_dwordx4 v[214:217], v[248:249], off offset:256
	global_load_dwordx4 v[218:221], v[250:251], off
	global_load_dwordx4 v[222:225], v[250:251], off offset:256
	global_load_dwordx4 v[226:229], v[252:253], off
	global_load_dwordx4 v[230:233], v[252:253], off offset:256
	global_load_dwordx4 v[234:237], v[174:175], off
	global_load_dwordx4 v[238:241], v[174:175], off offset:256
	s_waitcnt vmcnt(15)
	v_lshlrev_b32_e32 v168, 16, v178
	v_and_b32_e32 v169, 0xffff0000, v178
	v_lshlrev_b32_e32 v176, 16, v179
	v_and_b32_e32 v177, 0xffff0000, v179
	v_pk_add_f32 v[126:127], v[126:127], v[168:169]
	v_pk_add_f32 v[128:129], v[128:129], v[176:177]
	v_lshlrev_b32_e32 v168, 16, v180
	v_and_b32_e32 v169, 0xffff0000, v180
	v_lshlrev_b32_e32 v176, 16, v181
	v_and_b32_e32 v177, 0xffff0000, v181
	v_pk_add_f32 v[122:123], v[122:123], v[168:169]
	v_pk_add_f32 v[124:125], v[124:125], v[176:177]
	v_cvt_pk_bf16_f32 v178, v126, v127
	v_cvt_pk_bf16_f32 v179, v128, v129
	v_cvt_pk_bf16_f32 v180, v122, v123
	v_cvt_pk_bf16_f32 v181, v124, v125
	global_store_dwordx4 v[166:167], v[178:181], off
	s_waitcnt vmcnt(15)
	v_lshlrev_b32_e32 v168, 16, v182
	v_and_b32_e32 v169, 0xffff0000, v182
	v_lshlrev_b32_e32 v176, 16, v183
	v_and_b32_e32 v177, 0xffff0000, v183
	v_pk_add_f32 v[118:119], v[118:119], v[168:169]
	v_pk_add_f32 v[120:121], v[120:121], v[176:177]
	v_lshlrev_b32_e32 v168, 16, v184
	v_and_b32_e32 v169, 0xffff0000, v184
	v_lshlrev_b32_e32 v176, 16, v185
	v_and_b32_e32 v177, 0xffff0000, v185
	v_pk_add_f32 v[114:115], v[114:115], v[168:169]
	v_pk_add_f32 v[116:117], v[116:117], v[176:177]
	v_cvt_pk_bf16_f32 v182, v118, v119
	v_cvt_pk_bf16_f32 v183, v120, v121
	v_cvt_pk_bf16_f32 v184, v114, v115
	v_cvt_pk_bf16_f32 v185, v116, v117
	global_store_dwordx4 v[166:167], v[182:185], off offset:256
	s_waitcnt vmcnt(15)
	v_lshlrev_b32_e32 v168, 16, v186
	v_and_b32_e32 v169, 0xffff0000, v186
	v_lshlrev_b32_e32 v176, 16, v187
	v_and_b32_e32 v177, 0xffff0000, v187
	v_pk_add_f32 v[110:111], v[110:111], v[168:169]
	v_pk_add_f32 v[112:113], v[112:113], v[176:177]
	v_lshlrev_b32_e32 v168, 16, v188
	v_and_b32_e32 v169, 0xffff0000, v188
	v_lshlrev_b32_e32 v176, 16, v189
	v_and_b32_e32 v177, 0xffff0000, v189
	v_pk_add_f32 v[106:107], v[106:107], v[168:169]
	v_pk_add_f32 v[108:109], v[108:109], v[176:177]
	v_cvt_pk_bf16_f32 v186, v110, v111
	v_cvt_pk_bf16_f32 v187, v112, v113
	v_cvt_pk_bf16_f32 v188, v106, v107
	v_cvt_pk_bf16_f32 v189, v108, v109
	global_store_dwordx4 v[242:243], v[186:189], off
	s_waitcnt vmcnt(15)
	v_lshlrev_b32_e32 v168, 16, v190
	v_and_b32_e32 v169, 0xffff0000, v190
	v_lshlrev_b32_e32 v176, 16, v191
	v_and_b32_e32 v177, 0xffff0000, v191
	v_pk_add_f32 v[102:103], v[102:103], v[168:169]
	v_pk_add_f32 v[104:105], v[104:105], v[176:177]
	v_lshlrev_b32_e32 v168, 16, v192
	v_and_b32_e32 v169, 0xffff0000, v192
	v_lshlrev_b32_e32 v176, 16, v193
	v_and_b32_e32 v177, 0xffff0000, v193
	v_pk_add_f32 v[98:99], v[98:99], v[168:169]
	v_pk_add_f32 v[100:101], v[100:101], v[176:177]
	v_cvt_pk_bf16_f32 v190, v102, v103
	v_cvt_pk_bf16_f32 v191, v104, v105
	v_cvt_pk_bf16_f32 v192, v98, v99
	v_cvt_pk_bf16_f32 v193, v100, v101
	global_store_dwordx4 v[242:243], v[190:193], off offset:256
	s_waitcnt vmcnt(15)
	v_lshlrev_b32_e32 v168, 16, v194
	v_and_b32_e32 v169, 0xffff0000, v194
	v_lshlrev_b32_e32 v176, 16, v195
	v_and_b32_e32 v177, 0xffff0000, v195
	v_pk_add_f32 v[86:87], v[86:87], v[168:169]
	v_pk_add_f32 v[88:89], v[88:89], v[176:177]
	v_lshlrev_b32_e32 v168, 16, v196
	v_and_b32_e32 v169, 0xffff0000, v196
	v_lshlrev_b32_e32 v176, 16, v197
	v_and_b32_e32 v177, 0xffff0000, v197
	v_pk_add_f32 v[82:83], v[82:83], v[168:169]
	v_pk_add_f32 v[84:85], v[84:85], v[176:177]
	v_cvt_pk_bf16_f32 v194, v86, v87
	v_cvt_pk_bf16_f32 v195, v88, v89
	v_cvt_pk_bf16_f32 v196, v82, v83
	v_cvt_pk_bf16_f32 v197, v84, v85
	global_store_dwordx4 v[244:245], v[194:197], off
	s_waitcnt vmcnt(15)
	v_lshlrev_b32_e32 v168, 16, v198
	v_and_b32_e32 v169, 0xffff0000, v198
	v_lshlrev_b32_e32 v176, 16, v199
	v_and_b32_e32 v177, 0xffff0000, v199
	v_pk_add_f32 v[94:95], v[94:95], v[168:169]
	v_pk_add_f32 v[96:97], v[96:97], v[176:177]
	v_lshlrev_b32_e32 v168, 16, v200
	v_and_b32_e32 v169, 0xffff0000, v200
	v_lshlrev_b32_e32 v176, 16, v201
	v_and_b32_e32 v177, 0xffff0000, v201
	v_pk_add_f32 v[90:91], v[90:91], v[168:169]
	v_pk_add_f32 v[92:93], v[92:93], v[176:177]
	v_cvt_pk_bf16_f32 v198, v94, v95
	v_cvt_pk_bf16_f32 v199, v96, v97
	v_cvt_pk_bf16_f32 v200, v90, v91
	v_cvt_pk_bf16_f32 v201, v92, v93
	global_store_dwordx4 v[244:245], v[198:201], off offset:256
	s_waitcnt vmcnt(15)
; __device__ __forceinline__ unsigned pack2(float a, float b) { f32v2_t v = {a, b}; bf16v2_t r = __builtin_convertvector(v, bf16v2_t); return __builtin_bit_cast(unsigned, r); }
; template <int EPI, int N, int K>
; __device__ __forceinline__ void gemm_phase(const KP& p, int l, const bfr* A, const bfr* Bt) {
;     ...
;           int row = erow + ai * HM + wr * 64 + m * 16 + fr;
; #pragma unroll
;           for (int bj = 0; bj < 2; ++bj) {
;             u32x4* hp = (u32x4*)(hb + (size_t)row * DM + ecol + bj * HALF + wc * 32 + fq * 8);
;             u32x4 h = *hp, o;
; #pragma unroll
;             for (int q2 = 0; q2 < 4; ++q2) {
;               f32v2_t hv2 = {__uint_as_float(h[q2] << 16), __uint_as_float(h[q2] & 0xffff0000u)};
;               f32v2_t av2 = {acc[ai][bj][m][q2 >> 1][(q2 & 1) * 2], acc[ai][bj][m][q2 >> 1][(q2 & 1) * 2 + 1]};
;               f32v2_t s2 = hv2 + av2;
;               o[q2] = pack2(s2.x, s2.y);
;             }
;             *hp = o;
;           }
	v_lshlrev_b32_e32 v168, 16, v202
	v_and_b32_e32 v169, 0xffff0000, v202
	v_lshlrev_b32_e32 v176, 16, v203
	v_and_b32_e32 v177, 0xffff0000, v203
	v_pk_add_f32 v[78:79], v[78:79], v[168:169]
	v_pk_add_f32 v[80:81], v[80:81], v[176:177]
	v_lshlrev_b32_e32 v168, 16, v204
	v_and_b32_e32 v169, 0xffff0000, v204
	v_lshlrev_b32_e32 v176, 16, v205
	v_and_b32_e32 v177, 0xffff0000, v205
	v_pk_add_f32 v[74:75], v[74:75], v[168:169]
	v_pk_add_f32 v[76:77], v[76:77], v[176:177]
	v_cvt_pk_bf16_f32 v202, v78, v79
	v_cvt_pk_bf16_f32 v203, v80, v81
	v_cvt_pk_bf16_f32 v204, v74, v75
	v_cvt_pk_bf16_f32 v205, v76, v77
	global_store_dwordx4 v[246:247], v[202:205], off
	s_waitcnt vmcnt(15)
	v_lshlrev_b32_e32 v168, 16, v206
	v_and_b32_e32 v169, 0xffff0000, v206
	v_lshlrev_b32_e32 v176, 16, v207
	v_and_b32_e32 v177, 0xffff0000, v207
	v_pk_add_f32 v[70:71], v[70:71], v[168:169]
	v_pk_add_f32 v[72:73], v[72:73], v[176:177]
	v_lshlrev_b32_e32 v168, 16, v208
	v_and_b32_e32 v169, 0xffff0000, v208
	v_lshlrev_b32_e32 v176, 16, v209
	v_and_b32_e32 v177, 0xffff0000, v209
	v_pk_add_f32 v[66:67], v[66:67], v[168:169]
	v_pk_add_f32 v[68:69], v[68:69], v[176:177]
	v_cvt_pk_bf16_f32 v206, v70, v71
	v_cvt_pk_bf16_f32 v207, v72, v73
	v_cvt_pk_bf16_f32 v208, v66, v67
	v_cvt_pk_bf16_f32 v209, v68, v69
	global_store_dwordx4 v[246:247], v[206:209], off offset:256
	s_waitcnt vmcnt(15)
	v_lshlrev_b32_e32 v168, 16, v210
	v_and_b32_e32 v169, 0xffff0000, v210
	v_lshlrev_b32_e32 v176, 16, v211
	v_and_b32_e32 v177, 0xffff0000, v211
	v_pk_add_f32 v[62:63], v[62:63], v[168:169]
	v_pk_add_f32 v[64:65], v[64:65], v[176:177]
	v_lshlrev_b32_e32 v168, 16, v212
	v_and_b32_e32 v169, 0xffff0000, v212
	v_lshlrev_b32_e32 v176, 16, v213
	v_and_b32_e32 v177, 0xffff0000, v213
	v_pk_add_f32 v[58:59], v[58:59], v[168:169]
	v_pk_add_f32 v[60:61], v[60:61], v[176:177]
	v_cvt_pk_bf16_f32 v210, v62, v63
	v_cvt_pk_bf16_f32 v211, v64, v65
	v_cvt_pk_bf16_f32 v212, v58, v59
	v_cvt_pk_bf16_f32 v213, v60, v61
	global_store_dwordx4 v[248:249], v[210:213], off
	s_waitcnt vmcnt(15)
	v_lshlrev_b32_e32 v168, 16, v214
	v_and_b32_e32 v169, 0xffff0000, v214
	v_lshlrev_b32_e32 v176, 16, v215
	v_and_b32_e32 v177, 0xffff0000, v215
	v_pk_add_f32 v[54:55], v[54:55], v[168:169]
	v_pk_add_f32 v[56:57], v[56:57], v[176:177]
	v_lshlrev_b32_e32 v168, 16, v216
	v_and_b32_e32 v169, 0xffff0000, v216
	v_lshlrev_b32_e32 v176, 16, v217
	v_and_b32_e32 v177, 0xffff0000, v217
	v_pk_add_f32 v[50:51], v[50:51], v[168:169]
	v_pk_add_f32 v[52:53], v[52:53], v[176:177]
	v_cvt_pk_bf16_f32 v214, v54, v55
	v_cvt_pk_bf16_f32 v215, v56, v57
	v_cvt_pk_bf16_f32 v216, v50, v51
	v_cvt_pk_bf16_f32 v217, v52, v53
	global_store_dwordx4 v[248:249], v[214:217], off offset:256
	s_waitcnt vmcnt(15)
	v_lshlrev_b32_e32 v168, 16, v218
	v_and_b32_e32 v169, 0xffff0000, v218
	v_lshlrev_b32_e32 v176, 16, v219
	v_and_b32_e32 v177, 0xffff0000, v219
	v_pk_add_f32 v[46:47], v[46:47], v[168:169]
	v_pk_add_f32 v[48:49], v[48:49], v[176:177]
	v_lshlrev_b32_e32 v168, 16, v220
	v_and_b32_e32 v169, 0xffff0000, v220
	v_lshlrev_b32_e32 v176, 16, v221
	v_and_b32_e32 v177, 0xffff0000, v221
	v_pk_add_f32 v[42:43], v[42:43], v[168:169]
	v_pk_add_f32 v[44:45], v[44:45], v[176:177]
	v_cvt_pk_bf16_f32 v218, v46, v47
	v_cvt_pk_bf16_f32 v219, v48, v49
	v_cvt_pk_bf16_f32 v220, v42, v43
	v_cvt_pk_bf16_f32 v221, v44, v45
	global_store_dwordx4 v[250:251], v[218:221], off
	s_waitcnt vmcnt(15)
	v_lshlrev_b32_e32 v168, 16, v222
	v_and_b32_e32 v169, 0xffff0000, v222
	v_lshlrev_b32_e32 v176, 16, v223
	v_and_b32_e32 v177, 0xffff0000, v223
	v_pk_add_f32 v[38:39], v[38:39], v[168:169]
	v_pk_add_f32 v[40:41], v[40:41], v[176:177]
	v_lshlrev_b32_e32 v168, 16, v224
	v_and_b32_e32 v169, 0xffff0000, v224
	v_lshlrev_b32_e32 v176, 16, v225
	v_and_b32_e32 v177, 0xffff0000, v225
	v_pk_add_f32 v[34:35], v[34:35], v[168:169]
	v_pk_add_f32 v[36:37], v[36:37], v[176:177]
	v_cvt_pk_bf16_f32 v222, v38, v39
	v_cvt_pk_bf16_f32 v223, v40, v41
	v_cvt_pk_bf16_f32 v224, v34, v35
	v_cvt_pk_bf16_f32 v225, v36, v37
	global_store_dwordx4 v[250:251], v[222:225], off offset:256
	s_waitcnt vmcnt(15)
	v_lshlrev_b32_e32 v168, 16, v226
	v_and_b32_e32 v169, 0xffff0000, v226
	v_lshlrev_b32_e32 v176, 16, v227
	v_and_b32_e32 v177, 0xffff0000, v227
	v_pk_add_f32 v[30:31], v[30:31], v[168:169]
	v_pk_add_f32 v[32:33], v[32:33], v[176:177]
	v_lshlrev_b32_e32 v168, 16, v228
	v_and_b32_e32 v169, 0xffff0000, v228
	v_lshlrev_b32_e32 v176, 16, v229
	v_and_b32_e32 v177, 0xffff0000, v229
	v_pk_add_f32 v[26:27], v[26:27], v[168:169]
	v_pk_add_f32 v[28:29], v[28:29], v[176:177]
	v_cvt_pk_bf16_f32 v226, v30, v31
	v_cvt_pk_bf16_f32 v227, v32, v33
	v_cvt_pk_bf16_f32 v228, v26, v27
	v_cvt_pk_bf16_f32 v229, v28, v29
	global_store_dwordx4 v[252:253], v[226:229], off
	s_waitcnt vmcnt(15)
	v_lshlrev_b32_e32 v168, 16, v230
	v_and_b32_e32 v169, 0xffff0000, v230
	v_lshlrev_b32_e32 v176, 16, v231
	v_and_b32_e32 v177, 0xffff0000, v231
	v_pk_add_f32 v[22:23], v[22:23], v[168:169]
	v_pk_add_f32 v[24:25], v[24:25], v[176:177]
	v_lshlrev_b32_e32 v168, 16, v232
	v_and_b32_e32 v169, 0xffff0000, v232
	v_lshlrev_b32_e32 v176, 16, v233
	v_and_b32_e32 v177, 0xffff0000, v233
	v_pk_add_f32 v[18:19], v[18:19], v[168:169]
	v_pk_add_f32 v[20:21], v[20:21], v[176:177]
	v_cvt_pk_bf16_f32 v230, v22, v23
	v_cvt_pk_bf16_f32 v231, v24, v25
	v_cvt_pk_bf16_f32 v232, v18, v19
	v_cvt_pk_bf16_f32 v233, v20, v21
	global_store_dwordx4 v[252:253], v[230:233], off offset:256
	s_waitcnt vmcnt(15)
	v_lshlrev_b32_e32 v168, 16, v234
	v_and_b32_e32 v169, 0xffff0000, v234
	v_lshlrev_b32_e32 v176, 16, v235
	v_and_b32_e32 v177, 0xffff0000, v235
	v_pk_add_f32 v[14:15], v[14:15], v[168:169]
	v_pk_add_f32 v[16:17], v[16:17], v[176:177]
	v_lshlrev_b32_e32 v168, 16, v236
	v_and_b32_e32 v169, 0xffff0000, v236
	v_lshlrev_b32_e32 v176, 16, v237
	v_and_b32_e32 v177, 0xffff0000, v237
	v_pk_add_f32 v[10:11], v[10:11], v[168:169]
	v_pk_add_f32 v[12:13], v[12:13], v[176:177]
	v_cvt_pk_bf16_f32 v234, v14, v15
	v_cvt_pk_bf16_f32 v235, v16, v17
	v_cvt_pk_bf16_f32 v236, v10, v11
	v_cvt_pk_bf16_f32 v237, v12, v13
	global_store_dwordx4 v[174:175], v[234:237], off
	s_waitcnt vmcnt(15)
	v_lshlrev_b32_e32 v168, 16, v238
	v_and_b32_e32 v169, 0xffff0000, v238
	v_lshlrev_b32_e32 v176, 16, v239
	v_and_b32_e32 v177, 0xffff0000, v239
	v_pk_add_f32 v[6:7], v[6:7], v[168:169]
	v_pk_add_f32 v[8:9], v[8:9], v[176:177]
	v_lshlrev_b32_e32 v168, 16, v240
	v_and_b32_e32 v169, 0xffff0000, v240
	v_lshlrev_b32_e32 v176, 16, v241
	v_and_b32_e32 v177, 0xffff0000, v241
	v_pk_add_f32 v[2:3], v[2:3], v[168:169]
	v_pk_add_f32 v[4:5], v[4:5], v[176:177]
	v_cvt_pk_bf16_f32 v238, v6, v7
	v_cvt_pk_bf16_f32 v239, v8, v9
	v_cvt_pk_bf16_f32 v240, v2, v3
	v_cvt_pk_bf16_f32 v241, v4, v5
	global_store_dwordx4 v[174:175], v[238:241], off offset:256
	s_cbranch_vccz .LBB0_1167

; __device__ __forceinline__ unsigned pack2(float a, float b) { f32v2_t v = {a, b}; bf16v2_t r = __builtin_convertvector(v, bf16v2_t); return __builtin_bit_cast(unsigned, r); }
; template <int EPI, int N, int K>
; __device__ __forceinline__ void gemm_phase(const KP& p, int l, const bfr* A, const bfr* Bt) {
;     ...
;     } else if (EPI == 2) {
;       bfr* hb = (bfr*)(p.ws + OFF_HB);
; #pragma unroll
;       for (int ai = 0; ai < 2; ++ai)
; #pragma unroll
;         for (int m = 0; m < 4; ++m) {
;           int row = erow + ai * HM + wr * 64 + m * 16 + fr;
; #pragma unroll
;           for (int bj = 0; bj < 2; ++bj) {
;             u32x4* hp = (u32x4*)(hb + (size_t)row * DM + ecol + bj * HALF + wc * 32 + fq * 8);
;             u32x4 h = *hp, o;
; #pragma unroll
;             for (int q2 = 0; q2 < 4; ++q2) {
;               f32v2_t hv2 = {__uint_as_float(h[q2] << 16), __uint_as_float(h[q2] & 0xffff0000u)};
;               f32v2_t av2 = {acc[ai][bj][m][q2 >> 1][(q2 & 1) * 2], acc[ai][bj][m][q2 >> 1][(q2 & 1) * 2 + 1]};
;               f32v2_t s2 = hv2 + av2;
;               o[q2] = pack2(s2.x, s2.y);
;             }
;             *hp = o;
;           }
;         }
.LBB0_1128:
	v_add_u32_e32 v134, s2, v147
	v_ashrrev_i32_e32 v135, 31, v134
	v_lshl_add_u64 v[132:133], s[42:43], 1, v[130:131]
	v_lshlrev_b64 v[166:167], 11, v[134:135]
	v_lshl_add_u64 v[174:175], v[132:133], 0, v[166:167]
	s_andn2_b64 vcc, exec, s[0:1]
	s_mov_b32 s2, s14
	s_mov_b64 s[98:99], 0x8000
	s_mov_b64 s[100:101], 0x28000
	v_lshl_add_u64 v[242:243], v[174:175], 0, s[98:99]
	v_lshl_add_u64 v[244:245], v[242:243], 0, s[98:99]
	v_lshl_add_u64 v[246:247], v[244:245], 0, s[98:99]
	v_lshl_add_u64 v[248:249], v[246:247], 0, s[100:101]
	v_lshl_add_u64 v[250:251], v[248:249], 0, s[98:99]
	v_lshl_add_u64 v[252:253], v[250:251], 0, s[98:99]
	v_lshl_add_u64 v[166:167], v[252:253], 0, s[98:99]
	global_load_dwordx4 v[178:181], v[174:175], off
	global_load_dwordx4 v[182:185], v[174:175], off offset:256
	global_load_dwordx4 v[186:189], v[242:243], off
	global_load_dwordx4 v[190:193], v[242:243], off offset:256
	global_load_dwordx4 v[194:197], v[244:245], off
	global_load_dwordx4 v[198:201], v[244:245], off offset:256
	global_load_dwordx4 v[202:205], v[246:247], off
	global_load_dwordx4 v[206:209], v[246:247], off offset:256
	global_load_dwordx4 v[210:213], v[248:249], off
	global_load_dwordx4 v[214:217], v[248:249], off offset:256
	global_load_dwordx4 v[218:221], v[250:251], off
	global_load_dwordx4 v[222:225], v[250:251], off offset:256
	global_load_dwordx4 v[226:229], v[252:253], off
	global_load_dwordx4 v[230:233], v[252:253], off offset:256
	global_load_dwordx4 v[234:237], v[166:167], off
	global_load_dwordx4 v[238:241], v[166:167], off offset:256
	s_waitcnt vmcnt(15)
	v_lshlrev_b32_e32 v168, 16, v178
	v_and_b32_e32 v169, 0xffff0000, v178
	v_lshlrev_b32_e32 v176, 16, v179
	v_and_b32_e32 v177, 0xffff0000, v179
	v_pk_add_f32 v[126:127], v[126:127], v[168:169]
	v_pk_add_f32 v[128:129], v[128:129], v[176:177]
	v_lshlrev_b32_e32 v168, 16, v180
	v_and_b32_e32 v169, 0xffff0000, v180
	v_lshlrev_b32_e32 v176, 16, v181
	v_and_b32_e32 v177, 0xffff0000, v181
	v_pk_add_f32 v[122:123], v[122:123], v[168:169]
	v_pk_add_f32 v[124:125], v[124:125], v[176:177]
	v_cvt_pk_bf16_f32 v178, v126, v127
	v_cvt_pk_bf16_f32 v179, v128, v129
	v_cvt_pk_bf16_f32 v180, v122, v123
	v_cvt_pk_bf16_f32 v181, v124, v125
	global_store_dwordx4 v[174:175], v[178:181], off
	s_waitcnt vmcnt(15)
	v_lshlrev_b32_e32 v168, 16, v182
	v_and_b32_e32 v169, 0xffff0000, v182
	v_lshlrev_b32_e32 v176, 16, v183
	v_and_b32_e32 v177, 0xffff0000, v183
	v_pk_add_f32 v[118:119], v[118:119], v[168:169]
	v_pk_add_f32 v[120:121], v[120:121], v[176:177]
	v_lshlrev_b32_e32 v168, 16, v184
	v_and_b32_e32 v169, 0xffff0000, v184
	v_lshlrev_b32_e32 v176, 16, v185
	v_and_b32_e32 v177, 0xffff0000, v185
	v_pk_add_f32 v[114:115], v[114:115], v[168:169]
	v_pk_add_f32 v[116:117], v[116:117], v[176:177]
	v_cvt_pk_bf16_f32 v182, v118, v119
	v_cvt_pk_bf16_f32 v183, v120, v121
	v_cvt_pk_bf16_f32 v184, v114, v115
	v_cvt_pk_bf16_f32 v185, v116, v117
	global_store_dwordx4 v[174:175], v[182:185], off offset:256
	s_waitcnt vmcnt(15)
	v_lshlrev_b32_e32 v168, 16, v186
	v_and_b32_e32 v169, 0xffff0000, v186
	v_lshlrev_b32_e32 v176, 16, v187
	v_and_b32_e32 v177, 0xffff0000, v187
	v_pk_add_f32 v[110:111], v[110:111], v[168:169]
	v_pk_add_f32 v[112:113], v[112:113], v[176:177]
	v_lshlrev_b32_e32 v168, 16, v188
	v_and_b32_e32 v169, 0xffff0000, v188
	v_lshlrev_b32_e32 v176, 16, v189
	v_and_b32_e32 v177, 0xffff0000, v189
	v_pk_add_f32 v[106:107], v[106:107], v[168:169]
	v_pk_add_f32 v[108:109], v[108:109], v[176:177]
	v_cvt_pk_bf16_f32 v186, v110, v111
	v_cvt_pk_bf16_f32 v187, v112, v113
	v_cvt_pk_bf16_f32 v188, v106, v107
	v_cvt_pk_bf16_f32 v189, v108, v109
	global_store_dwordx4 v[242:243], v[186:189], off
	s_waitcnt vmcnt(15)
	v_lshlrev_b32_e32 v168, 16, v190
	v_and_b32_e32 v169, 0xffff0000, v190
	v_lshlrev_b32_e32 v176, 16, v191
	v_and_b32_e32 v177, 0xffff0000, v191
	v_pk_add_f32 v[102:103], v[102:103], v[168:169]
	v_pk_add_f32 v[104:105], v[104:105], v[176:177]
	v_lshlrev_b32_e32 v168, 16, v192
	v_and_b32_e32 v169, 0xffff0000, v192
	v_lshlrev_b32_e32 v176, 16, v193
	v_and_b32_e32 v177, 0xffff0000, v193
	v_pk_add_f32 v[98:99], v[98:99], v[168:169]
	v_pk_add_f32 v[100:101], v[100:101], v[176:177]
	v_cvt_pk_bf16_f32 v190, v102, v103
	v_cvt_pk_bf16_f32 v191, v104, v105
	v_cvt_pk_bf16_f32 v192, v98, v99
	v_cvt_pk_bf16_f32 v193, v100, v101
	global_store_dwordx4 v[242:243], v[190:193], off offset:256
	s_waitcnt vmcnt(15)
	v_lshlrev_b32_e32 v168, 16, v194
	v_and_b32_e32 v169, 0xffff0000, v194
	v_lshlrev_b32_e32 v176, 16, v195
	v_and_b32_e32 v177, 0xffff0000, v195
	v_pk_add_f32 v[86:87], v[86:87], v[168:169]
	v_pk_add_f32 v[88:89], v[88:89], v[176:177]
	v_lshlrev_b32_e32 v168, 16, v196
	v_and_b32_e32 v169, 0xffff0000, v196
	v_lshlrev_b32_e32 v176, 16, v197
	v_and_b32_e32 v177, 0xffff0000, v197
	v_pk_add_f32 v[82:83], v[82:83], v[168:169]
	v_pk_add_f32 v[84:85], v[84:85], v[176:177]
	v_cvt_pk_bf16_f32 v194, v86, v87
	v_cvt_pk_bf16_f32 v195, v88, v89
	v_cvt_pk_bf16_f32 v196, v82, v83
	v_cvt_pk_bf16_f32 v197, v84, v85
	global_store_dwordx4 v[244:245], v[194:197], off
	s_waitcnt vmcnt(15)
	v_lshlrev_b32_e32 v168, 16, v198
	v_and_b32_e32 v169, 0xffff0000, v198
	v_lshlrev_b32_e32 v176, 16, v199
	v_and_b32_e32 v177, 0xffff0000, v199
	v_pk_add_f32 v[94:95], v[94:95], v[168:169]
	v_pk_add_f32 v[96:97], v[96:97], v[176:177]
	v_lshlrev_b32_e32 v168, 16, v200
	v_and_b32_e32 v169, 0xffff0000, v200
	v_lshlrev_b32_e32 v176, 16, v201
	v_and_b32_e32 v177, 0xffff0000, v201
	v_pk_add_f32 v[90:91], v[90:91], v[168:169]
	v_pk_add_f32 v[92:93], v[92:93], v[176:177]
	v_cvt_pk_bf16_f32 v198, v94, v95
	v_cvt_pk_bf16_f32 v199, v96, v97
	v_cvt_pk_bf16_f32 v200, v90, v91
	v_cvt_pk_bf16_f32 v201, v92, v93
	global_store_dwordx4 v[244:245], v[198:201], off offset:256
	s_waitcnt vmcnt(15)
; __device__ __forceinline__ unsigned pack2(float a, float b) { f32v2_t v = {a, b}; bf16v2_t r = __builtin_convertvector(v, bf16v2_t); return __builtin_bit_cast(unsigned, r); }
; template <int EPI, int N, int K>
; __device__ __forceinline__ void gemm_phase(const KP& p, int l, const bfr* A, const bfr* Bt) {
;     ...
;           int row = erow + ai * HM + wr * 64 + m * 16 + fr;
; #pragma unroll
;           for (int bj = 0; bj < 2; ++bj) {
;             u32x4* hp = (u32x4*)(hb + (size_t)row * DM + ecol + bj * HALF + wc * 32 + fq * 8);
;             u32x4 h = *hp, o;
; #pragma unroll
;             for (int q2 = 0; q2 < 4; ++q2) {
;               f32v2_t hv2 = {__uint_as_float(h[q2] << 16), __uint_as_float(h[q2] & 0xffff0000u)};
;               f32v2_t av2 = {acc[ai][bj][m][q2 >> 1][(q2 & 1) * 2], acc[ai][bj][m][q2 >> 1][(q2 & 1) * 2 + 1]};
;               f32v2_t s2 = hv2 + av2;
;               o[q2] = pack2(s2.x, s2.y);
;             }
;             *hp = o;
;           }
	v_lshlrev_b32_e32 v168, 16, v202
	v_and_b32_e32 v169, 0xffff0000, v202
	v_lshlrev_b32_e32 v176, 16, v203
	v_and_b32_e32 v177, 0xffff0000, v203
	v_pk_add_f32 v[78:79], v[78:79], v[168:169]
	v_pk_add_f32 v[80:81], v[80:81], v[176:177]
	v_lshlrev_b32_e32 v168, 16, v204
	v_and_b32_e32 v169, 0xffff0000, v204
	v_lshlrev_b32_e32 v176, 16, v205
	v_and_b32_e32 v177, 0xffff0000, v205
	v_pk_add_f32 v[74:75], v[74:75], v[168:169]
	v_pk_add_f32 v[76:77], v[76:77], v[176:177]
	v_cvt_pk_bf16_f32 v202, v78, v79
	v_cvt_pk_bf16_f32 v203, v80, v81
	v_cvt_pk_bf16_f32 v204, v74, v75
	v_cvt_pk_bf16_f32 v205, v76, v77
	global_store_dwordx4 v[246:247], v[202:205], off
	s_waitcnt vmcnt(15)
	v_lshlrev_b32_e32 v168, 16, v206
	v_and_b32_e32 v169, 0xffff0000, v206
	v_lshlrev_b32_e32 v176, 16, v207
	v_and_b32_e32 v177, 0xffff0000, v207
	v_pk_add_f32 v[70:71], v[70:71], v[168:169]
	v_pk_add_f32 v[72:73], v[72:73], v[176:177]
	v_lshlrev_b32_e32 v168, 16, v208
	v_and_b32_e32 v169, 0xffff0000, v208
	v_lshlrev_b32_e32 v176, 16, v209
	v_and_b32_e32 v177, 0xffff0000, v209
	v_pk_add_f32 v[66:67], v[66:67], v[168:169]
	v_pk_add_f32 v[68:69], v[68:69], v[176:177]
	v_cvt_pk_bf16_f32 v206, v70, v71
	v_cvt_pk_bf16_f32 v207, v72, v73
	v_cvt_pk_bf16_f32 v208, v66, v67
	v_cvt_pk_bf16_f32 v209, v68, v69
	global_store_dwordx4 v[246:247], v[206:209], off offset:256
	s_waitcnt vmcnt(15)
	v_lshlrev_b32_e32 v168, 16, v210
	v_and_b32_e32 v169, 0xffff0000, v210
	v_lshlrev_b32_e32 v176, 16, v211
	v_and_b32_e32 v177, 0xffff0000, v211
	v_pk_add_f32 v[62:63], v[62:63], v[168:169]
	v_pk_add_f32 v[64:65], v[64:65], v[176:177]
	v_lshlrev_b32_e32 v168, 16, v212
	v_and_b32_e32 v169, 0xffff0000, v212
	v_lshlrev_b32_e32 v176, 16, v213
	v_and_b32_e32 v177, 0xffff0000, v213
	v_pk_add_f32 v[58:59], v[58:59], v[168:169]
	v_pk_add_f32 v[60:61], v[60:61], v[176:177]
	v_cvt_pk_bf16_f32 v210, v62, v63
	v_cvt_pk_bf16_f32 v211, v64, v65
	v_cvt_pk_bf16_f32 v212, v58, v59
	v_cvt_pk_bf16_f32 v213, v60, v61
	global_store_dwordx4 v[248:249], v[210:213], off
	s_waitcnt vmcnt(15)
	v_lshlrev_b32_e32 v168, 16, v214
	v_and_b32_e32 v169, 0xffff0000, v214
	v_lshlrev_b32_e32 v176, 16, v215
	v_and_b32_e32 v177, 0xffff0000, v215
	v_pk_add_f32 v[54:55], v[54:55], v[168:169]
	v_pk_add_f32 v[56:57], v[56:57], v[176:177]
	v_lshlrev_b32_e32 v168, 16, v216
	v_and_b32_e32 v169, 0xffff0000, v216
	v_lshlrev_b32_e32 v176, 16, v217
	v_and_b32_e32 v177, 0xffff0000, v217
	v_pk_add_f32 v[50:51], v[50:51], v[168:169]
	v_pk_add_f32 v[52:53], v[52:53], v[176:177]
	v_cvt_pk_bf16_f32 v214, v54, v55
	v_cvt_pk_bf16_f32 v215, v56, v57
	v_cvt_pk_bf16_f32 v216, v50, v51
	v_cvt_pk_bf16_f32 v217, v52, v53
	global_store_dwordx4 v[248:249], v[214:217], off offset:256
	s_waitcnt vmcnt(15)
	v_lshlrev_b32_e32 v168, 16, v218
	v_and_b32_e32 v169, 0xffff0000, v218
	v_lshlrev_b32_e32 v176, 16, v219
	v_and_b32_e32 v177, 0xffff0000, v219
	v_pk_add_f32 v[46:47], v[46:47], v[168:169]
	v_pk_add_f32 v[48:49], v[48:49], v[176:177]
	v_lshlrev_b32_e32 v168, 16, v220
	v_and_b32_e32 v169, 0xffff0000, v220
	v_lshlrev_b32_e32 v176, 16, v221
	v_and_b32_e32 v177, 0xffff0000, v221
	v_pk_add_f32 v[42:43], v[42:43], v[168:169]
	v_pk_add_f32 v[44:45], v[44:45], v[176:177]
	v_cvt_pk_bf16_f32 v218, v46, v47
	v_cvt_pk_bf16_f32 v219, v48, v49
	v_cvt_pk_bf16_f32 v220, v42, v43
	v_cvt_pk_bf16_f32 v221, v44, v45
	global_store_dwordx4 v[250:251], v[218:221], off
	s_waitcnt vmcnt(15)
	v_lshlrev_b32_e32 v168, 16, v222
	v_and_b32_e32 v169, 0xffff0000, v222
	v_lshlrev_b32_e32 v176, 16, v223
	v_and_b32_e32 v177, 0xffff0000, v223
	v_pk_add_f32 v[38:39], v[38:39], v[168:169]
	v_pk_add_f32 v[40:41], v[40:41], v[176:177]
	v_lshlrev_b32_e32 v168, 16, v224
	v_and_b32_e32 v169, 0xffff0000, v224
	v_lshlrev_b32_e32 v176, 16, v225
	v_and_b32_e32 v177, 0xffff0000, v225
	v_pk_add_f32 v[34:35], v[34:35], v[168:169]
	v_pk_add_f32 v[36:37], v[36:37], v[176:177]
	v_cvt_pk_bf16_f32 v222, v38, v39
	v_cvt_pk_bf16_f32 v223, v40, v41
	v_cvt_pk_bf16_f32 v224, v34, v35
	v_cvt_pk_bf16_f32 v225, v36, v37
	global_store_dwordx4 v[250:251], v[222:225], off offset:256
	s_waitcnt vmcnt(15)
	v_lshlrev_b32_e32 v168, 16, v226
	v_and_b32_e32 v169, 0xffff0000, v226
	v_lshlrev_b32_e32 v176, 16, v227
	v_and_b32_e32 v177, 0xffff0000, v227
	v_pk_add_f32 v[30:31], v[30:31], v[168:169]
	v_pk_add_f32 v[32:33], v[32:33], v[176:177]
	v_lshlrev_b32_e32 v168, 16, v228
	v_and_b32_e32 v169, 0xffff0000, v228
	v_lshlrev_b32_e32 v176, 16, v229
	v_and_b32_e32 v177, 0xffff0000, v229
	v_pk_add_f32 v[26:27], v[26:27], v[168:169]
	v_pk_add_f32 v[28:29], v[28:29], v[176:177]
	v_cvt_pk_bf16_f32 v226, v30, v31
	v_cvt_pk_bf16_f32 v227, v32, v33
	v_cvt_pk_bf16_f32 v228, v26, v27
	v_cvt_pk_bf16_f32 v229, v28, v29
	global_store_dwordx4 v[252:253], v[226:229], off
	s_waitcnt vmcnt(15)
	v_lshlrev_b32_e32 v168, 16, v230
	v_and_b32_e32 v169, 0xffff0000, v230
	v_lshlrev_b32_e32 v176, 16, v231
	v_and_b32_e32 v177, 0xffff0000, v231
	v_pk_add_f32 v[22:23], v[22:23], v[168:169]
	v_pk_add_f32 v[24:25], v[24:25], v[176:177]
	v_lshlrev_b32_e32 v168, 16, v232
	v_and_b32_e32 v169, 0xffff0000, v232
	v_lshlrev_b32_e32 v176, 16, v233
	v_and_b32_e32 v177, 0xffff0000, v233
	v_pk_add_f32 v[18:19], v[18:19], v[168:169]
	v_pk_add_f32 v[20:21], v[20:21], v[176:177]
	v_cvt_pk_bf16_f32 v230, v22, v23
	v_cvt_pk_bf16_f32 v231, v24, v25
	v_cvt_pk_bf16_f32 v232, v18, v19
	v_cvt_pk_bf16_f32 v233, v20, v21
	global_store_dwordx4 v[252:253], v[230:233], off offset:256
	s_waitcnt vmcnt(15)
	v_lshlrev_b32_e32 v168, 16, v234
	v_and_b32_e32 v169, 0xffff0000, v234
	v_lshlrev_b32_e32 v176, 16, v235
	v_and_b32_e32 v177, 0xffff0000, v235
	v_pk_add_f32 v[14:15], v[14:15], v[168:169]
	v_pk_add_f32 v[16:17], v[16:17], v[176:177]
	v_lshlrev_b32_e32 v168, 16, v236
	v_and_b32_e32 v169, 0xffff0000, v236
	v_lshlrev_b32_e32 v176, 16, v237
	v_and_b32_e32 v177, 0xffff0000, v237
	v_pk_add_f32 v[10:11], v[10:11], v[168:169]
	v_pk_add_f32 v[12:13], v[12:13], v[176:177]
	v_cvt_pk_bf16_f32 v234, v14, v15
	v_cvt_pk_bf16_f32 v235, v16, v17
	v_cvt_pk_bf16_f32 v236, v10, v11
	v_cvt_pk_bf16_f32 v237, v12, v13
	global_store_dwordx4 v[166:167], v[234:237], off
	s_waitcnt vmcnt(15)
	v_lshlrev_b32_e32 v168, 16, v238
	v_and_b32_e32 v169, 0xffff0000, v238
	v_lshlrev_b32_e32 v176, 16, v239
	v_and_b32_e32 v177, 0xffff0000, v239
	v_pk_add_f32 v[6:7], v[6:7], v[168:169]
	v_pk_add_f32 v[8:9], v[8:9], v[176:177]
	v_lshlrev_b32_e32 v168, 16, v240
	v_and_b32_e32 v169, 0xffff0000, v240
	v_lshlrev_b32_e32 v176, 16, v241
	v_and_b32_e32 v177, 0xffff0000, v241
	v_pk_add_f32 v[2:3], v[2:3], v[168:169]
	v_pk_add_f32 v[4:5], v[4:5], v[176:177]
	v_cvt_pk_bf16_f32 v238, v6, v7
	v_cvt_pk_bf16_f32 v239, v8, v9
	v_cvt_pk_bf16_f32 v240, v2, v3
	v_cvt_pk_bf16_f32 v241, v4, v5
	global_store_dwordx4 v[166:167], v[238:241], off offset:256
	s_cbranch_vccz .LBB0_1137

; #define LAS __attribute__((address_space(3)))
; __global__ void __launch_bounds__(512, 2) hymba_fwd(KP p) {
;   extern __shared__ __attribute__((aligned(16))) unsigned char smem[];
;   volatile LAS unsigned* st = (volatile LAS unsigned*)(smem + 131072);
;   if (threadIdx.x == 0) { st[0] = 0u; st[1] = 0u; }
;   __syncthreads();
;   XcdBarrier xb = xcd_barrier_post((unsigned*)(p.ws + OFF_BAR), st);
;   for (int ph = p.ph_lo; ph < p.ph_hi; ++ph) {
;     run_phase(p, ph);
;     if (ph + 1 < p.ph_hi) { if (ph < 0) cg::this_grid().sync(); else xcd_barrier(xb); }
;   }
; }
	.amdhsa_kernel _Z9hymba_fwd2KP
		.amdhsa_group_segment_fixed_size 0
		.amdhsa_private_segment_fixed_size 0
		.amdhsa_kernarg_size 496
		.amdhsa_user_sgpr_count 2
		.amdhsa_user_sgpr_dispatch_ptr 0
		.amdhsa_user_sgpr_queue_ptr 0
		.amdhsa_user_sgpr_kernarg_segment_ptr 1
		.amdhsa_user_sgpr_dispatch_id 0
		.amdhsa_user_sgpr_kernarg_preload_length 0
		.amdhsa_user_sgpr_kernarg_preload_offset 0
		.amdhsa_user_sgpr_private_segment_size 0
		.amdhsa_uses_dynamic_stack 0
		.amdhsa_enable_private_segment 0
		.amdhsa_system_sgpr_workgroup_id_x 1
		.amdhsa_system_sgpr_workgroup_id_y 0
		.amdhsa_system_sgpr_workgroup_id_z 0
		.amdhsa_system_sgpr_workgroup_info 0
		.amdhsa_system_vgpr_workitem_id 2
		.amdhsa_next_free_vgpr 256
		.amdhsa_next_free_sgpr 102
		.amdhsa_accum_offset 256
		.amdhsa_reserve_vcc 1
		.amdhsa_float_round_mode_32 0
		.amdhsa_float_round_mode_16_64 0
		.amdhsa_float_denorm_mode_32 3
		.amdhsa_float_denorm_mode_16_64 3
		.amdhsa_dx10_clamp 1
		.amdhsa_ieee_mode 1
		.amdhsa_fp16_overflow 0
		.amdhsa_tg_split 0
		.amdhsa_exception_fp_ieee_invalid_op 0
		.amdhsa_exception_fp_denorm_src 0
		.amdhsa_exception_fp_ieee_div_zero 0
		.amdhsa_exception_fp_ieee_overflow 0
		.amdhsa_exception_fp_ieee_underflow 0
		.amdhsa_exception_fp_ieee_inexact 0
		.amdhsa_exception_int_div_zero 0
	.end_amdhsa_kernel

; #define LAS __attribute__((address_space(3)))
; __global__ void __launch_bounds__(512, 2) hymba_fwd(KP p) {
;   extern __shared__ __attribute__((aligned(16))) unsigned char smem[];
;   volatile LAS unsigned* st = (volatile LAS unsigned*)(smem + 131072);
;   if (threadIdx.x == 0) { st[0] = 0u; st[1] = 0u; }
;   __syncthreads();
;   XcdBarrier xb = xcd_barrier_post((unsigned*)(p.ws + OFF_BAR), st);
;   for (int ph = p.ph_lo; ph < p.ph_hi; ++ph) {
;     run_phase(p, ph);
;     if (ph + 1 < p.ph_hi) { if (ph < 0) cg::this_grid().sync(); else xcd_barrier(xb); }
;   }
; }
amdhsa.kernels:
  - .agpr_count:     0
    .args:
      - .offset:         0
        .size:           240
        .value_kind:     by_value
      - .offset:         240
        .size:           4
        .value_kind:     hidden_block_count_x
      - .offset:         244
        .size:           4
        .value_kind:     hidden_block_count_y
      - .offset:         248
        .size:           4
        .value_kind:     hidden_block_count_z
      - .offset:         252
        .size:           2
        .value_kind:     hidden_group_size_x
      - .offset:         254
        .size:           2
        .value_kind:     hidden_group_size_y
      - .offset:         256
        .size:           2
        .value_kind:     hidden_group_size_z
      - .offset:         258
        .size:           2
        .value_kind:     hidden_remainder_x
      - .offset:         260
        .size:           2
        .value_kind:     hidden_remainder_y
      - .offset:         262
        .size:           2
        .value_kind:     hidden_remainder_z
      - .offset:         280
        .size:           8
        .value_kind:     hidden_global_offset_x
      - .offset:         288
        .size:           8
        .value_kind:     hidden_global_offset_y
      - .offset:         296
        .size:           8
        .value_kind:     hidden_global_offset_z
      - .offset:         304
        .size:           2
        .value_kind:     hidden_grid_dims
      - .offset:         328
        .size:           8
        .value_kind:     hidden_multigrid_sync_arg
      - .offset:         360
        .size:           4
        .value_kind:     hidden_dynamic_lds_size
    .group_segment_fixed_size: 0
    .kernarg_segment_align: 8
    .kernarg_segment_size: 496
    .language:       OpenCL C
    .language_version:
      - 2
      - 0
    .max_flat_workgroup_size: 512
    .name:           _Z9hymba_fwd2KP
    .private_segment_fixed_size: 0
    .sgpr_count:     108
    .sgpr_spill_count: 142
    .symbol:         _Z9hymba_fwd2KP.kd
    .uniform_work_group_size: 1
    .uses_dynamic_stack: false
    .vgpr_count:     256
    .vgpr_spill_count: 0
    .wavefront_size: 64
